# redundant s_waitcnt lgkmcnt(0) behind the K-loop barriers removed (the one before the barrier already covers it)
# baseline (speedup 1.0000x reference)
.LBB0_236:
	s_add_i32 s12, s75, 2
	s_add_u32 s30, s28, 0xfff00080
	s_addc_u32 s31, s29, -1
	s_cmp_eq_u32 s72, s75
	s_cselect_b32 s35, s68, s31
	s_cselect_b32 s34, s69, s30
	s_cselect_b32 s31, s70, s74
	s_cselect_b32 s30, s71, s73
	s_cmpk_lt_i32 s3, 0x56
	s_cselect_b32 s36, s58, 0x2b00
	s_mov_b32 s37, 0xac00
	s_cselect_b32 s75, s37, 0x4000
	s_sub_i32 s36, s36, s33
	v_min3_i32 v5, s36, v174, 2
	v_sub_u32_e32 v174, v174, v5
	v_readfirstlane_b32 s78, v5
	s_max_i32 s36, s78, 0
	s_add_i32 s36, s33, s36
	s_add_i32 s76, s36, -1
	s_min_i32 s36, s33, s76
	s_mul_hi_i32 s37, s75, s36
	s_mul_i32 s36, s75, s36
	s_add_u32 s36, s38, s36
	s_addc_u32 s37, s39, s37
	s_mul_hi_i32 s77, s75, s76
	s_mul_i32 s75, s75, s76
	s_add_u32 s76, s38, s75
	global_load_dwordx4 v[152:155], v173, s[36:37] nt
	s_addc_u32 s77, s39, s77
	global_load_dwordx4 v[164:167], v173, s[76:77] nt
	s_add_i32 s33, s78, s33
	ds_read_b128 v[168:171], v160
	ds_read_b128 v[176:179], v160 offset:1024
	ds_read_b128 v[180:183], v160 offset:2048
	ds_read_b128 v[184:187], v160 offset:3072
	ds_read_b128 v[188:191], v160 offset:16384
	ds_read_b128 v[192:195], v160 offset:17408
	ds_read_b128 v[196:199], v160 offset:18432
	ds_read_b128 v[200:203], v160 offset:19456
	s_add_i32 m0, s49, 0xc000
	ds_read_b128 v[204:207], v163
	ds_read_b128 v[208:211], v163 offset:1024
	ds_read_b128 v[212:215], v163 offset:2048
	ds_read_b128 v[216:219], v163 offset:3072
	ds_read_b128 v[220:223], v163 offset:4096
	ds_read_b128 v[224:227], v163 offset:5120
	ds_read_b128 v[228:231], v163 offset:6144
	global_load_lds_dwordx4 v146, s[28:29]
	s_add_i32 m0, s49, 0xe000
	ds_read_b128 v[236:239], v163 offset:7168
	global_load_lds_dwordx4 v148, s[28:29]
	s_waitcnt vmcnt(10)
	s_waitcnt lgkmcnt(0)
	s_barrier
	s_setprio 1
	v_mfma_f32_16x16x32_bf16 v[132:135], v[168:171], v[204:207], v[132:135]
	v_mfma_f32_16x16x32_bf16 v[128:131], v[180:183], v[204:207], v[128:131]
	v_mfma_f32_16x16x32_bf16 v[116:119], v[168:171], v[212:215], v[116:119]
	v_mfma_f32_16x16x32_bf16 v[112:115], v[180:183], v[212:215], v[112:115]
	v_mfma_f32_16x16x32_bf16 v[100:103], v[168:171], v[220:223], v[100:103]
	v_mfma_f32_16x16x32_bf16 v[96:99], v[180:183], v[220:223], v[96:99]
	v_mfma_f32_16x16x32_bf16 v[84:87], v[168:171], v[228:231], v[84:87]
	v_mfma_f32_16x16x32_bf16 v[80:83], v[180:183], v[228:231], v[80:83]
	v_mfma_f32_16x16x32_bf16 v[132:135], v[176:179], v[208:211], v[132:135]
	v_mfma_f32_16x16x32_bf16 v[128:131], v[184:187], v[208:211], v[128:131]
	v_mfma_f32_16x16x32_bf16 v[116:119], v[176:179], v[216:219], v[116:119]
	v_mfma_f32_16x16x32_bf16 v[112:115], v[184:187], v[216:219], v[112:115]
	v_mfma_f32_16x16x32_bf16 v[100:103], v[176:179], v[224:227], v[100:103]
	v_mfma_f32_16x16x32_bf16 v[96:99], v[184:187], v[224:227], v[96:99]
	v_mfma_f32_16x16x32_bf16 v[84:87], v[176:179], v[236:239], v[84:87]
	v_mfma_f32_16x16x32_bf16 v[80:83], v[184:187], v[236:239], v[80:83]
	s_setprio 0
	s_setprio 1
	v_mfma_f32_16x16x32_bf16 v[124:127], v[188:191], v[204:207], v[124:127]
	v_mfma_f32_16x16x32_bf16 v[120:123], v[196:199], v[204:207], v[120:123]
	v_mfma_f32_16x16x32_bf16 v[108:111], v[188:191], v[212:215], v[108:111]
	v_mfma_f32_16x16x32_bf16 v[104:107], v[196:199], v[212:215], v[104:107]
	v_mfma_f32_16x16x32_bf16 v[92:95], v[188:191], v[220:223], v[92:95]
	v_mfma_f32_16x16x32_bf16 v[88:91], v[196:199], v[220:223], v[88:91]
	v_mfma_f32_16x16x32_bf16 v[76:79], v[188:191], v[228:231], v[76:79]
	v_mfma_f32_16x16x32_bf16 v[72:75], v[196:199], v[228:231], v[72:75]
	v_mfma_f32_16x16x32_bf16 v[124:127], v[192:195], v[208:211], v[124:127]
	v_mfma_f32_16x16x32_bf16 v[120:123], v[200:203], v[208:211], v[120:123]
	v_mfma_f32_16x16x32_bf16 v[108:111], v[192:195], v[216:219], v[108:111]
	v_mfma_f32_16x16x32_bf16 v[104:107], v[200:203], v[216:219], v[104:107]
	v_mfma_f32_16x16x32_bf16 v[92:95], v[192:195], v[224:227], v[92:95]
	v_mfma_f32_16x16x32_bf16 v[88:91], v[200:203], v[224:227], v[88:91]
	v_mfma_f32_16x16x32_bf16 v[76:79], v[192:195], v[236:239], v[76:79]
	v_mfma_f32_16x16x32_bf16 v[72:75], v[200:203], v[236:239], v[72:75]
	s_setprio 0
	s_barrier
	s_add_i32 s36, s59, s48
	s_mov_b32 m0, s36
	ds_read_b128 v[204:207], v163 offset:16384
	ds_read_b128 v[208:211], v163 offset:17408
	ds_read_b128 v[212:215], v163 offset:18432
	ds_read_b128 v[216:219], v163 offset:19456
	global_load_lds_dwordx4 v138, s[30:31]
	s_add_i32 m0, s36, 0x2000
	s_add_u32 s36, s30, 0x100000
	s_addc_u32 s37, s31, 0
	s_add_i32 s75, s60, s48
	global_load_lds_dwordx4 v142, s[30:31]
	s_mov_b32 m0, s75
	ds_read_b128 v[236:239], v163 offset:23552
	global_load_lds_dwordx4 v138, s[36:37]
	s_add_i32 m0, s75, 0x2000
	ds_read_b128 v[228:231], v163 offset:22528
	global_load_lds_dwordx4 v142, s[36:37]
	s_mov_b32 m0, s49
	ds_read_b128 v[224:227], v163 offset:21504
	global_load_lds_dwordx4 v136, s[34:35]
	s_mov_b32 m0, s50
	ds_read_b128 v[220:223], v163 offset:20480
	global_load_lds_dwordx4 v140, s[34:35]
	s_waitcnt vmcnt(10)
	s_waitcnt lgkmcnt(0)
	s_barrier
	s_setprio 1
	v_mfma_f32_16x16x32_bf16 v[68:71], v[168:171], v[204:207], v[68:71]
	v_mfma_f32_16x16x32_bf16 v[64:67], v[180:183], v[204:207], v[64:67]
	v_mfma_f32_16x16x32_bf16 v[52:55], v[168:171], v[212:215], v[52:55]
	v_mfma_f32_16x16x32_bf16 v[48:51], v[180:183], v[212:215], v[48:51]
	v_mfma_f32_16x16x32_bf16 v[36:39], v[168:171], v[220:223], v[36:39]
	v_mfma_f32_16x16x32_bf16 v[32:35], v[180:183], v[220:223], v[32:35]
	v_mfma_f32_16x16x32_bf16 v[20:23], v[168:171], v[228:231], v[20:23]
	v_mfma_f32_16x16x32_bf16 v[16:19], v[180:183], v[228:231], v[16:19]
	v_mfma_f32_16x16x32_bf16 v[68:71], v[176:179], v[208:211], v[68:71]
	v_mfma_f32_16x16x32_bf16 v[64:67], v[184:187], v[208:211], v[64:67]
	v_mfma_f32_16x16x32_bf16 v[52:55], v[176:179], v[216:219], v[52:55]
	v_mfma_f32_16x16x32_bf16 v[48:51], v[184:187], v[216:219], v[48:51]
	v_mfma_f32_16x16x32_bf16 v[36:39], v[176:179], v[224:227], v[36:39]
	v_mfma_f32_16x16x32_bf16 v[32:35], v[184:187], v[224:227], v[32:35]
	v_mfma_f32_16x16x32_bf16 v[20:23], v[176:179], v[236:239], v[20:23]
	v_mfma_f32_16x16x32_bf16 v[16:19], v[184:187], v[236:239], v[16:19]
	s_setprio 0
	s_setprio 1
	v_mfma_f32_16x16x32_bf16 v[60:63], v[188:191], v[204:207], v[60:63]
	v_mfma_f32_16x16x32_bf16 v[56:59], v[196:199], v[204:207], v[56:59]
	v_mfma_f32_16x16x32_bf16 v[44:47], v[188:191], v[212:215], v[44:47]
	v_mfma_f32_16x16x32_bf16 v[40:43], v[196:199], v[212:215], v[40:43]
	v_mfma_f32_16x16x32_bf16 v[28:31], v[188:191], v[220:223], v[28:31]
	v_mfma_f32_16x16x32_bf16 v[24:27], v[196:199], v[220:223], v[24:27]
	v_mfma_f32_16x16x32_bf16 v[12:15], v[188:191], v[228:231], v[12:15]
	v_mfma_f32_16x16x32_bf16 v[6:9], v[196:199], v[228:231], v[8:11]
	v_mfma_f32_16x16x32_bf16 v[60:63], v[192:195], v[208:211], v[60:63]
	v_mfma_f32_16x16x32_bf16 v[56:59], v[200:203], v[208:211], v[56:59]
	v_mfma_f32_16x16x32_bf16 v[44:47], v[192:195], v[216:219], v[44:47]
	v_mfma_f32_16x16x32_bf16 v[40:43], v[200:203], v[216:219], v[40:43]
	v_mfma_f32_16x16x32_bf16 v[28:31], v[192:195], v[224:227], v[28:31]
	v_mfma_f32_16x16x32_bf16 v[24:27], v[200:203], v[224:227], v[24:27]
	v_mfma_f32_16x16x32_bf16 v[12:15], v[192:195], v[236:239], v[12:15]
	v_mfma_f32_16x16x32_bf16 v[6:9], v[200:203], v[236:239], v[6:9]
	s_setprio 0
	s_barrier
	s_add_i32 s36, 0, 0x18000
	s_add_i32 s37, 0, 0x1c000
	ds_read_b128 v[168:171], v160 offset:32768
	ds_read_b128 v[176:179], v160 offset:33792
	ds_read_b128 v[180:183], v160 offset:34816
	ds_read_b128 v[184:187], v160 offset:35840
	ds_read_b128 v[188:191], v160 offset:49152
	ds_read_b128 v[192:195], v160 offset:50176
	ds_read_b128 v[196:199], v160 offset:51200
	ds_read_b128 v[200:203], v160 offset:52224
	s_add_u32 s34, s34, 0x100000
	s_addc_u32 s35, s35, 0
	s_mov_b32 m0, s51
	ds_read_b128 v[204:207], v163 offset:32768
	ds_read_b128 v[208:211], v163 offset:33792
	ds_read_b128 v[212:215], v163 offset:34816
	ds_read_b128 v[216:219], v163 offset:35840
	ds_read_b128 v[220:223], v163 offset:36864
	ds_read_b128 v[224:227], v163 offset:37888
	ds_read_b128 v[228:231], v163 offset:38912
	global_load_lds_dwordx4 v136, s[34:35]
	s_mov_b32 m0, s52
	ds_read_b128 v[236:239], v163 offset:39936
	global_load_lds_dwordx4 v140, s[34:35]
	s_waitcnt vmcnt(8)
	s_waitcnt lgkmcnt(0)
	s_barrier
	s_setprio 1
	v_mfma_f32_16x16x32_bf16 v[132:135], v[168:171], v[204:207], v[132:135]
	v_mfma_f32_16x16x32_bf16 v[128:131], v[180:183], v[204:207], v[128:131]
	v_mfma_f32_16x16x32_bf16 v[116:119], v[168:171], v[212:215], v[116:119]
	v_mfma_f32_16x16x32_bf16 v[112:115], v[180:183], v[212:215], v[112:115]
	v_mfma_f32_16x16x32_bf16 v[100:103], v[168:171], v[220:223], v[100:103]
	v_max3_f32 v0, v0, |v152|, |v164|
	v_mfma_f32_16x16x32_bf16 v[96:99], v[180:183], v[220:223], v[96:99]
	v_max3_f32 v1, v1, |v153|, |v165|
	v_mfma_f32_16x16x32_bf16 v[84:87], v[168:171], v[228:231], v[84:87]
	v_max3_f32 v2, v2, |v154|, |v166|
	v_mfma_f32_16x16x32_bf16 v[80:83], v[180:183], v[228:231], v[80:83]
	v_max3_f32 v3, v3, |v155|, |v167|
	v_mfma_f32_16x16x32_bf16 v[132:135], v[176:179], v[208:211], v[132:135]
	v_mfma_f32_16x16x32_bf16 v[128:131], v[184:187], v[208:211], v[128:131]
	v_mfma_f32_16x16x32_bf16 v[116:119], v[176:179], v[216:219], v[116:119]
	v_mfma_f32_16x16x32_bf16 v[112:115], v[184:187], v[216:219], v[112:115]
	v_mfma_f32_16x16x32_bf16 v[100:103], v[176:179], v[224:227], v[100:103]
	v_mfma_f32_16x16x32_bf16 v[96:99], v[184:187], v[224:227], v[96:99]
	v_mfma_f32_16x16x32_bf16 v[84:87], v[176:179], v[236:239], v[84:87]
	v_mfma_f32_16x16x32_bf16 v[80:83], v[184:187], v[236:239], v[80:83]
	s_setprio 0
	s_setprio 1
	v_mfma_f32_16x16x32_bf16 v[124:127], v[188:191], v[204:207], v[124:127]
	v_mfma_f32_16x16x32_bf16 v[120:123], v[196:199], v[204:207], v[120:123]
	v_mfma_f32_16x16x32_bf16 v[108:111], v[188:191], v[212:215], v[108:111]
	v_mfma_f32_16x16x32_bf16 v[104:107], v[196:199], v[212:215], v[104:107]
	v_mfma_f32_16x16x32_bf16 v[92:95], v[188:191], v[220:223], v[92:95]
	v_mfma_f32_16x16x32_bf16 v[88:91], v[196:199], v[220:223], v[88:91]
	v_mfma_f32_16x16x32_bf16 v[76:79], v[188:191], v[228:231], v[76:79]
	v_mfma_f32_16x16x32_bf16 v[72:75], v[196:199], v[228:231], v[72:75]
	v_mfma_f32_16x16x32_bf16 v[124:127], v[192:195], v[208:211], v[124:127]
	v_mfma_f32_16x16x32_bf16 v[120:123], v[200:203], v[208:211], v[120:123]
	v_mfma_f32_16x16x32_bf16 v[108:111], v[192:195], v[216:219], v[108:111]
	v_mfma_f32_16x16x32_bf16 v[104:107], v[200:203], v[216:219], v[104:107]
	v_mfma_f32_16x16x32_bf16 v[92:95], v[192:195], v[224:227], v[92:95]
	v_mfma_f32_16x16x32_bf16 v[88:91], v[200:203], v[224:227], v[88:91]
	v_mfma_f32_16x16x32_bf16 v[76:79], v[192:195], v[236:239], v[76:79]
	v_mfma_f32_16x16x32_bf16 v[72:75], v[200:203], v[236:239], v[72:75]
	s_setprio 0
	s_barrier
	s_add_u32 s98, s30, s10
	s_addc_u32 s99, s31, s11
	s_add_u32 s100, s34, s10
	s_addc_u32 s101, s35, s11
	s_sub_u32 s100, s100, 0x100000
	s_subb_u32 s101, s101, 0
	s_add_i32 s34, s36, s48
	s_mov_b32 m0, s34
	ds_read_b128 v[152:155], v163 offset:49152
	ds_read_b128 v[164:167], v163 offset:50176
	ds_read_b128 v[204:207], v163 offset:51200
	ds_read_b128 v[208:211], v163 offset:52224
	global_load_lds_dwordx4 v138, s[98:99]
	s_add_i32 m0, s34, 0x2000
	s_add_u32 s30, s30, 0x100080
	s_addc_u32 s31, s31, 0
	s_add_i32 s34, s37, s48
	global_load_lds_dwordx4 v142, s[98:99]
	s_mov_b32 m0, s34
	ds_read_b128 v[224:227], v163 offset:56320
	global_load_lds_dwordx4 v138, s[30:31]
	s_add_i32 m0, s34, 0x2000
	ds_read_b128 v[220:223], v163 offset:55296
	global_load_lds_dwordx4 v142, s[30:31]
	s_mov_b32 m0, s56
	ds_read_b128 v[216:219], v163 offset:54272
	global_load_lds_dwordx4 v136, s[100:101]
	s_mov_b32 m0, s57
	ds_read_b128 v[212:215], v163 offset:53248
	global_load_lds_dwordx4 v140, s[100:101]
	s_waitcnt vmcnt(8)
	s_waitcnt lgkmcnt(0)
	s_barrier
	s_setprio 1
	v_mfma_f32_16x16x32_bf16 v[68:71], v[168:171], v[152:155], v[68:71]
	v_mfma_f32_16x16x32_bf16 v[64:67], v[180:183], v[152:155], v[64:67]
	v_mfma_f32_16x16x32_bf16 v[52:55], v[168:171], v[204:207], v[52:55]
	v_mfma_f32_16x16x32_bf16 v[48:51], v[180:183], v[204:207], v[48:51]
	v_mfma_f32_16x16x32_bf16 v[36:39], v[168:171], v[212:215], v[36:39]
	v_mfma_f32_16x16x32_bf16 v[32:35], v[180:183], v[212:215], v[32:35]
	v_mfma_f32_16x16x32_bf16 v[20:23], v[168:171], v[220:223], v[20:23]
	v_mfma_f32_16x16x32_bf16 v[16:19], v[180:183], v[220:223], v[16:19]
	v_mfma_f32_16x16x32_bf16 v[68:71], v[176:179], v[164:167], v[68:71]
	v_mfma_f32_16x16x32_bf16 v[64:67], v[184:187], v[164:167], v[64:67]
	v_mfma_f32_16x16x32_bf16 v[52:55], v[176:179], v[208:211], v[52:55]
	v_mfma_f32_16x16x32_bf16 v[48:51], v[184:187], v[208:211], v[48:51]
	v_mfma_f32_16x16x32_bf16 v[36:39], v[176:179], v[216:219], v[36:39]
	v_mfma_f32_16x16x32_bf16 v[32:35], v[184:187], v[216:219], v[32:35]
	v_mfma_f32_16x16x32_bf16 v[20:23], v[176:179], v[224:227], v[20:23]
	v_mfma_f32_16x16x32_bf16 v[16:19], v[184:187], v[224:227], v[16:19]
	s_setprio 0
	s_setprio 1
	v_mfma_f32_16x16x32_bf16 v[60:63], v[188:191], v[152:155], v[60:63]
	v_mfma_f32_16x16x32_bf16 v[56:59], v[196:199], v[152:155], v[56:59]
	v_mfma_f32_16x16x32_bf16 v[44:47], v[188:191], v[204:207], v[44:47]
	v_mfma_f32_16x16x32_bf16 v[40:43], v[196:199], v[204:207], v[40:43]
	v_mfma_f32_16x16x32_bf16 v[28:31], v[188:191], v[212:215], v[28:31]
	v_mfma_f32_16x16x32_bf16 v[24:27], v[196:199], v[212:215], v[24:27]
	v_mfma_f32_16x16x32_bf16 v[10:13], v[188:191], v[220:223], v[12:15]
	v_mfma_f32_16x16x32_bf16 v[6:9], v[196:199], v[220:223], v[6:9]
	v_mfma_f32_16x16x32_bf16 v[60:63], v[192:195], v[164:167], v[60:63]
	v_mfma_f32_16x16x32_bf16 v[56:59], v[200:203], v[164:167], v[56:59]
	v_mfma_f32_16x16x32_bf16 v[44:47], v[192:195], v[208:211], v[44:47]
	v_mfma_f32_16x16x32_bf16 v[40:43], v[200:203], v[208:211], v[40:43]
	v_mfma_f32_16x16x32_bf16 v[28:31], v[192:195], v[216:219], v[28:31]
	v_mfma_f32_16x16x32_bf16 v[24:27], v[200:203], v[216:219], v[24:27]
	v_mfma_f32_16x16x32_bf16 v[12:15], v[192:195], v[224:227], v[10:13]
	v_mfma_f32_16x16x32_bf16 v[8:11], v[200:203], v[224:227], v[6:9]
	s_setprio 0
	s_barrier
	s_add_u32 s28, s28, 0x100
	s_addc_u32 s29, s29, 0
	s_add_u32 s73, s73, 0x100
	s_addc_u32 s74, s74, 0
	s_cmp_ge_i32 s12, s67
	s_cbranch_scc0 .LBB0_221
	s_and_b64 vcc, exec, s[14:15]
	s_cbranch_vccz .LBB0_239

.Lp1i_body:
	s_add_i32 s8, s74, 2
	s_add_u32 s34, s30, 0xfff80080
	s_addc_u32 s35, s31, -1
	s_cmp_eq_u32 s71, s74
	s_cselect_b32 s37, s67, s35
	s_cselect_b32 s36, s68, s34
	s_cselect_b32 s35, s69, s73
	s_cselect_b32 s34, s70, s72
	ds_read_b128 v[160:163], v177
	ds_read_b128 v[164:167], v177 offset:1024
	ds_read_b128 v[168:171], v177 offset:2048
	ds_read_b128 v[182:185], v177 offset:3072
	ds_read_b128 v[186:189], v177 offset:16384
	ds_read_b128 v[190:193], v177 offset:17408
	ds_read_b128 v[194:197], v177 offset:18432
	ds_read_b128 v[198:201], v177 offset:19456
	s_add_i32 m0, s46, 0xc000
	ds_read_b128 v[202:205], v180
	ds_read_b128 v[206:209], v180 offset:1024
	ds_read_b128 v[210:213], v180 offset:2048
	ds_read_b128 v[214:217], v180 offset:3072
	ds_read_b128 v[218:221], v180 offset:4096
	ds_read_b128 v[222:225], v180 offset:5120
	ds_read_b128 v[226:229], v180 offset:6144
	global_load_lds_dwordx4 v146, s[30:31]
	s_add_i32 m0, s46, 0xe000
	ds_read_b128 v[230:233], v180 offset:7168
	global_load_lds_dwordx4 v148, s[30:31]
	s_waitcnt vmcnt(8)
	s_waitcnt lgkmcnt(0)
	s_barrier
	s_setprio 1
	v_mfma_i32_16x16x64_i8 v[132:135], v[160:163], v[202:205], v[132:135]
	v_mfma_i32_16x16x64_i8 v[128:131], v[168:171], v[202:205], v[128:131]
	v_mfma_i32_16x16x64_i8 v[124:127], v[160:163], v[210:213], v[124:127]
	v_mfma_i32_16x16x64_i8 v[120:123], v[168:171], v[210:213], v[120:123]
	v_mfma_i32_16x16x64_i8 v[112:115], v[160:163], v[218:221], v[112:115]
	v_mfma_i32_16x16x64_i8 v[104:107], v[168:171], v[218:221], v[104:107]
	v_mfma_i32_16x16x64_i8 v[96:99], v[160:163], v[226:229], v[96:99]
	v_mfma_i32_16x16x64_i8 v[88:91], v[168:171], v[226:229], v[88:91]
	v_mfma_i32_16x16x64_i8 v[132:135], v[164:167], v[206:209], v[132:135]
	v_mfma_i32_16x16x64_i8 v[128:131], v[182:185], v[206:209], v[128:131]
	v_mfma_i32_16x16x64_i8 v[124:127], v[164:167], v[214:217], v[124:127]
	v_mfma_i32_16x16x64_i8 v[120:123], v[182:185], v[214:217], v[120:123]
	v_mfma_i32_16x16x64_i8 v[112:115], v[164:167], v[222:225], v[112:115]
	v_mfma_i32_16x16x64_i8 v[104:107], v[182:185], v[222:225], v[104:107]
	v_mfma_i32_16x16x64_i8 v[96:99], v[164:167], v[230:233], v[96:99]
	v_mfma_i32_16x16x64_i8 v[88:91], v[182:185], v[230:233], v[88:91]
	s_setprio 0
	s_setprio 1
	v_mfma_i32_16x16x64_i8 v[116:119], v[186:189], v[202:205], v[116:119]
	v_mfma_i32_16x16x64_i8 v[108:111], v[194:197], v[202:205], v[108:111]
	v_mfma_i32_16x16x64_i8 v[100:103], v[186:189], v[210:213], v[100:103]
	v_mfma_i32_16x16x64_i8 v[92:95], v[194:197], v[210:213], v[92:95]
	v_mfma_i32_16x16x64_i8 v[84:87], v[186:189], v[218:221], v[84:87]
	v_mfma_i32_16x16x64_i8 v[80:83], v[194:197], v[218:221], v[80:83]
	v_mfma_i32_16x16x64_i8 v[76:79], v[186:189], v[226:229], v[76:79]
	v_mfma_i32_16x16x64_i8 v[72:75], v[194:197], v[226:229], v[72:75]
	v_mfma_i32_16x16x64_i8 v[116:119], v[190:193], v[206:209], v[116:119]
	v_mfma_i32_16x16x64_i8 v[108:111], v[198:201], v[206:209], v[108:111]
	v_mfma_i32_16x16x64_i8 v[100:103], v[190:193], v[214:217], v[100:103]
	v_mfma_i32_16x16x64_i8 v[92:95], v[198:201], v[214:217], v[92:95]
	v_mfma_i32_16x16x64_i8 v[84:87], v[190:193], v[222:225], v[84:87]
	v_mfma_i32_16x16x64_i8 v[80:83], v[198:201], v[222:225], v[80:83]
	v_mfma_i32_16x16x64_i8 v[76:79], v[190:193], v[230:233], v[76:79]
	v_mfma_i32_16x16x64_i8 v[72:75], v[198:201], v[230:233], v[72:75]
	s_setprio 0
	s_barrier
	s_add_i32 s74, s57, s45
	s_mov_b32 m0, s74
	ds_read_b128 v[202:205], v180 offset:16384
	ds_read_b128 v[206:209], v180 offset:17408
	ds_read_b128 v[210:213], v180 offset:18432
	ds_read_b128 v[214:217], v180 offset:19456
	global_load_lds_dwordx4 v138, s[34:35]
	s_add_i32 m0, s74, 0x2000
	s_add_u32 s74, s34, 0x80000
	s_addc_u32 s75, s35, 0
	s_add_i32 s76, s58, s45
	global_load_lds_dwordx4 v142, s[34:35]
	s_mov_b32 m0, s76
	ds_read_b128 v[230:233], v180 offset:23552
	global_load_lds_dwordx4 v138, s[74:75]
	s_add_i32 m0, s76, 0x2000
	ds_read_b128 v[226:229], v180 offset:22528
	global_load_lds_dwordx4 v142, s[74:75]
	s_mov_b32 m0, s46
	ds_read_b128 v[222:225], v180 offset:21504
	global_load_lds_dwordx4 v136, s[36:37]
	s_mov_b32 m0, s47
	ds_read_b128 v[218:221], v180 offset:20480
	global_load_lds_dwordx4 v140, s[36:37]
	s_waitcnt vmcnt(8)
	s_waitcnt lgkmcnt(0)
	s_barrier
	s_setprio 1
	v_mfma_i32_16x16x64_i8 v[68:71], v[160:163], v[202:205], v[68:71]
	v_mfma_i32_16x16x64_i8 v[64:67], v[168:171], v[202:205], v[64:67]
	v_mfma_i32_16x16x64_i8 v[60:63], v[160:163], v[210:213], v[60:63]
	v_mfma_i32_16x16x64_i8 v[56:59], v[168:171], v[210:213], v[56:59]
	v_mfma_i32_16x16x64_i8 v[48:51], v[160:163], v[218:221], v[48:51]
	v_mfma_i32_16x16x64_i8 v[40:43], v[168:171], v[218:221], v[40:43]
	v_mfma_i32_16x16x64_i8 v[32:35], v[160:163], v[226:229], v[32:35]
	v_mfma_i32_16x16x64_i8 v[24:27], v[168:171], v[226:229], v[24:27]
	v_mfma_i32_16x16x64_i8 v[68:71], v[164:167], v[206:209], v[68:71]
	v_mfma_i32_16x16x64_i8 v[64:67], v[182:185], v[206:209], v[64:67]
	v_mfma_i32_16x16x64_i8 v[60:63], v[164:167], v[214:217], v[60:63]
	v_mfma_i32_16x16x64_i8 v[56:59], v[182:185], v[214:217], v[56:59]
	v_mfma_i32_16x16x64_i8 v[48:51], v[164:167], v[222:225], v[48:51]
	v_mfma_i32_16x16x64_i8 v[40:43], v[182:185], v[222:225], v[40:43]
	v_mfma_i32_16x16x64_i8 v[32:35], v[164:167], v[230:233], v[32:35]
	v_mfma_i32_16x16x64_i8 v[24:27], v[182:185], v[230:233], v[24:27]
	s_setprio 0
	s_setprio 1
	v_mfma_i32_16x16x64_i8 v[52:55], v[186:189], v[202:205], v[52:55]
	v_mfma_i32_16x16x64_i8 v[44:47], v[194:197], v[202:205], v[44:47]
	v_mfma_i32_16x16x64_i8 v[36:39], v[186:189], v[210:213], v[36:39]
	v_mfma_i32_16x16x64_i8 v[28:31], v[194:197], v[210:213], v[28:31]
	v_mfma_i32_16x16x64_i8 v[20:23], v[186:189], v[218:221], v[20:23]
	v_mfma_i32_16x16x64_i8 v[16:19], v[194:197], v[218:221], v[16:19]
	v_mfma_i32_16x16x64_i8 v[12:15], v[186:189], v[226:229], v[12:15]
	v_mfma_i32_16x16x64_i8 v[6:9], v[194:197], v[226:229], v[8:11]
	v_mfma_i32_16x16x64_i8 v[52:55], v[190:193], v[206:209], v[52:55]
	v_mfma_i32_16x16x64_i8 v[44:47], v[198:201], v[206:209], v[44:47]
	v_mfma_i32_16x16x64_i8 v[36:39], v[190:193], v[214:217], v[36:39]
	v_mfma_i32_16x16x64_i8 v[28:31], v[198:201], v[214:217], v[28:31]
	v_mfma_i32_16x16x64_i8 v[20:23], v[190:193], v[222:225], v[20:23]
	v_mfma_i32_16x16x64_i8 v[16:19], v[198:201], v[222:225], v[16:19]
	v_mfma_i32_16x16x64_i8 v[12:15], v[190:193], v[230:233], v[12:15]
	v_mfma_i32_16x16x64_i8 v[6:9], v[198:201], v[230:233], v[6:9]
	s_setprio 0
	s_barrier
	s_add_i32 s74, 0, 0x18000
	s_add_i32 s75, 0, 0x1c000
	ds_read_b128 v[160:163], v177 offset:32768
	ds_read_b128 v[164:167], v177 offset:33792
	ds_read_b128 v[168:171], v177 offset:34816
	ds_read_b128 v[182:185], v177 offset:35840
	ds_read_b128 v[186:189], v177 offset:49152
	ds_read_b128 v[190:193], v177 offset:50176
	ds_read_b128 v[194:197], v177 offset:51200
	ds_read_b128 v[198:201], v177 offset:52224
	s_add_u32 s36, s36, 0x80000
	s_addc_u32 s37, s37, 0
	s_mov_b32 m0, s48
	ds_read_b128 v[202:205], v180 offset:32768
	ds_read_b128 v[206:209], v180 offset:33792
	ds_read_b128 v[210:213], v180 offset:34816
	ds_read_b128 v[214:217], v180 offset:35840
	ds_read_b128 v[218:221], v180 offset:36864
	ds_read_b128 v[222:225], v180 offset:37888
	ds_read_b128 v[226:229], v180 offset:38912
	global_load_lds_dwordx4 v136, s[36:37]
	s_mov_b32 m0, s49
	ds_read_b128 v[230:233], v180 offset:39936
	global_load_lds_dwordx4 v140, s[36:37]
	s_waitcnt vmcnt(8)
	s_waitcnt lgkmcnt(0)
	s_barrier
	s_setprio 1
	v_mfma_i32_16x16x64_i8 v[132:135], v[160:163], v[202:205], v[132:135]
	v_mfma_i32_16x16x64_i8 v[128:131], v[168:171], v[202:205], v[128:131]
	v_mfma_i32_16x16x64_i8 v[124:127], v[160:163], v[210:213], v[124:127]
	v_mfma_i32_16x16x64_i8 v[120:123], v[168:171], v[210:213], v[120:123]
	v_mfma_i32_16x16x64_i8 v[112:115], v[160:163], v[218:221], v[112:115]
	v_mfma_i32_16x16x64_i8 v[104:107], v[168:171], v[218:221], v[104:107]
	v_mfma_i32_16x16x64_i8 v[96:99], v[160:163], v[226:229], v[96:99]
	v_mfma_i32_16x16x64_i8 v[88:91], v[168:171], v[226:229], v[88:91]
	v_mfma_i32_16x16x64_i8 v[132:135], v[164:167], v[206:209], v[132:135]
	v_mfma_i32_16x16x64_i8 v[128:131], v[182:185], v[206:209], v[128:131]
	v_mfma_i32_16x16x64_i8 v[124:127], v[164:167], v[214:217], v[124:127]
	v_mfma_i32_16x16x64_i8 v[120:123], v[182:185], v[214:217], v[120:123]
	v_mfma_i32_16x16x64_i8 v[112:115], v[164:167], v[222:225], v[112:115]
	v_mfma_i32_16x16x64_i8 v[104:107], v[182:185], v[222:225], v[104:107]
	v_mfma_i32_16x16x64_i8 v[96:99], v[164:167], v[230:233], v[96:99]
	v_mfma_i32_16x16x64_i8 v[88:91], v[182:185], v[230:233], v[88:91]
	s_setprio 0
	s_setprio 1
	v_mfma_i32_16x16x64_i8 v[116:119], v[186:189], v[202:205], v[116:119]
	v_mfma_i32_16x16x64_i8 v[108:111], v[194:197], v[202:205], v[108:111]
	v_mfma_i32_16x16x64_i8 v[100:103], v[186:189], v[210:213], v[100:103]
	v_mfma_i32_16x16x64_i8 v[92:95], v[194:197], v[210:213], v[92:95]
	v_mfma_i32_16x16x64_i8 v[84:87], v[186:189], v[218:221], v[84:87]
	v_mfma_i32_16x16x64_i8 v[80:83], v[194:197], v[218:221], v[80:83]
	v_mfma_i32_16x16x64_i8 v[76:79], v[186:189], v[226:229], v[76:79]
	v_mfma_i32_16x16x64_i8 v[72:75], v[194:197], v[226:229], v[72:75]
	v_mfma_i32_16x16x64_i8 v[116:119], v[190:193], v[206:209], v[116:119]
	v_mfma_i32_16x16x64_i8 v[108:111], v[198:201], v[206:209], v[108:111]
	v_mfma_i32_16x16x64_i8 v[100:103], v[190:193], v[214:217], v[100:103]
	v_mfma_i32_16x16x64_i8 v[92:95], v[198:201], v[214:217], v[92:95]
	v_mfma_i32_16x16x64_i8 v[84:87], v[190:193], v[222:225], v[84:87]
	v_mfma_i32_16x16x64_i8 v[80:83], v[198:201], v[222:225], v[80:83]
	v_mfma_i32_16x16x64_i8 v[76:79], v[190:193], v[230:233], v[76:79]
	v_mfma_i32_16x16x64_i8 v[72:75], v[198:201], v[230:233], v[72:75]
	s_setprio 0
	s_barrier
	s_add_u32 s98, s34, s14
	s_addc_u32 s99, s35, s15
	s_add_u32 s100, s36, s14
	s_addc_u32 s101, s37, s15
	s_sub_u32 s100, s100, 0x80000
	s_subb_u32 s101, s101, 0
	s_add_i32 s36, s74, s45
	s_mov_b32 m0, s36
	ds_read_b128 v[152:155], v180 offset:49152
	ds_read_b128 v[156:159], v180 offset:50176
	ds_read_b128 v[202:205], v180 offset:51200
	ds_read_b128 v[206:209], v180 offset:52224
	global_load_lds_dwordx4 v138, s[98:99]
	s_add_i32 m0, s36, 0x2000
	s_add_u32 s34, s34, 0x80080
	s_addc_u32 s35, s35, 0
	s_add_i32 s36, s75, s45
	global_load_lds_dwordx4 v142, s[98:99]
	s_mov_b32 m0, s36
	ds_read_b128 v[222:225], v180 offset:56320
	global_load_lds_dwordx4 v138, s[34:35]
	s_add_i32 m0, s36, 0x2000
	ds_read_b128 v[218:221], v180 offset:55296
	global_load_lds_dwordx4 v142, s[34:35]
	s_mov_b32 m0, s54
	ds_read_b128 v[214:217], v180 offset:54272
	global_load_lds_dwordx4 v136, s[100:101]
	s_mov_b32 m0, s55
	ds_read_b128 v[210:213], v180 offset:53248
	global_load_lds_dwordx4 v140, s[100:101]
	s_waitcnt vmcnt(8)
	s_waitcnt lgkmcnt(0)
	s_barrier
	s_setprio 1
	v_mfma_i32_16x16x64_i8 v[68:71], v[160:163], v[152:155], v[68:71]
	v_mfma_i32_16x16x64_i8 v[64:67], v[168:171], v[152:155], v[64:67]
	v_mfma_i32_16x16x64_i8 v[60:63], v[160:163], v[202:205], v[60:63]
	v_mfma_i32_16x16x64_i8 v[56:59], v[168:171], v[202:205], v[56:59]
	v_mfma_i32_16x16x64_i8 v[48:51], v[160:163], v[210:213], v[48:51]
	v_mfma_i32_16x16x64_i8 v[40:43], v[168:171], v[210:213], v[40:43]
	v_mfma_i32_16x16x64_i8 v[32:35], v[160:163], v[218:221], v[32:35]
	v_mfma_i32_16x16x64_i8 v[24:27], v[168:171], v[218:221], v[24:27]
	v_mfma_i32_16x16x64_i8 v[68:71], v[164:167], v[156:159], v[68:71]
	v_mfma_i32_16x16x64_i8 v[64:67], v[182:185], v[156:159], v[64:67]
	v_mfma_i32_16x16x64_i8 v[60:63], v[164:167], v[206:209], v[60:63]
	v_mfma_i32_16x16x64_i8 v[56:59], v[182:185], v[206:209], v[56:59]
	v_mfma_i32_16x16x64_i8 v[48:51], v[164:167], v[214:217], v[48:51]
	v_mfma_i32_16x16x64_i8 v[40:43], v[182:185], v[214:217], v[40:43]
	v_mfma_i32_16x16x64_i8 v[32:35], v[164:167], v[222:225], v[32:35]
	v_mfma_i32_16x16x64_i8 v[24:27], v[182:185], v[222:225], v[24:27]
	s_setprio 0
	s_setprio 1
	v_mfma_i32_16x16x64_i8 v[52:55], v[186:189], v[152:155], v[52:55]
	v_mfma_i32_16x16x64_i8 v[44:47], v[194:197], v[152:155], v[44:47]
	v_mfma_i32_16x16x64_i8 v[36:39], v[186:189], v[202:205], v[36:39]
	v_mfma_i32_16x16x64_i8 v[28:31], v[194:197], v[202:205], v[28:31]
	v_mfma_i32_16x16x64_i8 v[20:23], v[186:189], v[210:213], v[20:23]
	v_mfma_i32_16x16x64_i8 v[16:19], v[194:197], v[210:213], v[16:19]
	v_mfma_i32_16x16x64_i8 v[10:13], v[186:189], v[218:221], v[12:15]
	v_mfma_i32_16x16x64_i8 v[6:9], v[194:197], v[218:221], v[6:9]
	v_mfma_i32_16x16x64_i8 v[52:55], v[190:193], v[156:159], v[52:55]
	v_mfma_i32_16x16x64_i8 v[44:47], v[198:201], v[156:159], v[44:47]
	v_mfma_i32_16x16x64_i8 v[36:39], v[190:193], v[206:209], v[36:39]
	v_mfma_i32_16x16x64_i8 v[28:31], v[198:201], v[206:209], v[28:31]
	v_mfma_i32_16x16x64_i8 v[20:23], v[190:193], v[214:217], v[20:23]
	v_mfma_i32_16x16x64_i8 v[16:19], v[198:201], v[214:217], v[16:19]
	v_mfma_i32_16x16x64_i8 v[12:15], v[190:193], v[222:225], v[10:13]
	v_mfma_i32_16x16x64_i8 v[8:11], v[198:201], v[222:225], v[6:9]
	s_setprio 0
	s_barrier
	s_add_u32 s30, s30, 0x100
	s_addc_u32 s31, s31, 0
	s_add_u32 s72, s72, 0x100
	s_addc_u32 s73, s73, 0
	s_cmp_ge_i32 s8, s66
	s_cbranch_scc0 .Lp1i_top
	s_branch .Lp1i_epi

.LBB0_327:
	s_add_i32 s8, s74, 2
	s_add_u32 s34, s30, 0xfff80080
	s_addc_u32 s35, s31, -1
	s_cmp_eq_u32 s71, s74
	s_cselect_b32 s37, s67, s35
	s_cselect_b32 s36, s68, s34
	s_cselect_b32 s35, s69, s73
	s_cselect_b32 s34, s70, s72
	s_cmpk_lt_i32 s3, 0x56
	s_cselect_b32 s74, s56, 0x2b00
	s_mov_b32 s75, 0xac00
	s_cselect_b32 s76, s75, 0x4000
	s_sub_i32 s74, s74, s33
	v_min3_i32 v5, s74, v174, 2
	v_sub_u32_e32 v174, v174, v5
	v_readfirstlane_b32 s78, v5
	s_max_i32 s74, s78, 0
	s_add_i32 s74, s33, s74
	s_add_i32 s77, s74, -1
	s_min_i32 s74, s33, s77
	s_mul_hi_i32 s75, s76, s74
	s_mul_i32 s74, s76, s74
	s_add_u32 s74, s38, s74
	s_addc_u32 s75, s39, s75
	s_mul_hi_i32 s79, s76, s77
	s_mul_i32 s76, s76, s77
	s_add_u32 s76, s38, s76
	global_load_dwordx4 v[152:155], v173, s[74:75] nt
	s_addc_u32 s77, s39, s79
	global_load_dwordx4 v[156:159], v173, s[76:77] nt
	s_add_i32 s33, s78, s33
	ds_read_b128 v[160:163], v177
	ds_read_b128 v[164:167], v177 offset:1024
	ds_read_b128 v[168:171], v177 offset:2048
	ds_read_b128 v[182:185], v177 offset:3072
	ds_read_b128 v[186:189], v177 offset:16384
	ds_read_b128 v[190:193], v177 offset:17408
	ds_read_b128 v[194:197], v177 offset:18432
	ds_read_b128 v[198:201], v177 offset:19456
	s_add_i32 m0, s46, 0xc000
	ds_read_b128 v[202:205], v180
	ds_read_b128 v[206:209], v180 offset:1024
	ds_read_b128 v[210:213], v180 offset:2048
	ds_read_b128 v[214:217], v180 offset:3072
	ds_read_b128 v[218:221], v180 offset:4096
	ds_read_b128 v[222:225], v180 offset:5120
	ds_read_b128 v[226:229], v180 offset:6144
	global_load_lds_dwordx4 v146, s[30:31]
	s_add_i32 m0, s46, 0xe000
	ds_read_b128 v[230:233], v180 offset:7168
	global_load_lds_dwordx4 v148, s[30:31]
	s_waitcnt vmcnt(10)
	s_waitcnt lgkmcnt(0)
	s_barrier
	s_setprio 1
	v_mfma_i32_16x16x64_i8 v[132:135], v[160:163], v[202:205], v[132:135]
	v_mfma_i32_16x16x64_i8 v[128:131], v[168:171], v[202:205], v[128:131]
	v_mfma_i32_16x16x64_i8 v[124:127], v[160:163], v[210:213], v[124:127]
	v_mfma_i32_16x16x64_i8 v[120:123], v[168:171], v[210:213], v[120:123]
	v_mfma_i32_16x16x64_i8 v[112:115], v[160:163], v[218:221], v[112:115]
	v_mfma_i32_16x16x64_i8 v[104:107], v[168:171], v[218:221], v[104:107]
	v_mfma_i32_16x16x64_i8 v[96:99], v[160:163], v[226:229], v[96:99]
	v_mfma_i32_16x16x64_i8 v[88:91], v[168:171], v[226:229], v[88:91]
	v_mfma_i32_16x16x64_i8 v[132:135], v[164:167], v[206:209], v[132:135]
	v_mfma_i32_16x16x64_i8 v[128:131], v[182:185], v[206:209], v[128:131]
	v_mfma_i32_16x16x64_i8 v[124:127], v[164:167], v[214:217], v[124:127]
	v_mfma_i32_16x16x64_i8 v[120:123], v[182:185], v[214:217], v[120:123]
	v_mfma_i32_16x16x64_i8 v[112:115], v[164:167], v[222:225], v[112:115]
	v_mfma_i32_16x16x64_i8 v[104:107], v[182:185], v[222:225], v[104:107]
	v_mfma_i32_16x16x64_i8 v[96:99], v[164:167], v[230:233], v[96:99]
	v_mfma_i32_16x16x64_i8 v[88:91], v[182:185], v[230:233], v[88:91]
	s_setprio 0
	s_setprio 1
	v_mfma_i32_16x16x64_i8 v[116:119], v[186:189], v[202:205], v[116:119]
	v_mfma_i32_16x16x64_i8 v[108:111], v[194:197], v[202:205], v[108:111]
	v_mfma_i32_16x16x64_i8 v[100:103], v[186:189], v[210:213], v[100:103]
	v_mfma_i32_16x16x64_i8 v[92:95], v[194:197], v[210:213], v[92:95]
	v_mfma_i32_16x16x64_i8 v[84:87], v[186:189], v[218:221], v[84:87]
	v_mfma_i32_16x16x64_i8 v[80:83], v[194:197], v[218:221], v[80:83]
	v_mfma_i32_16x16x64_i8 v[76:79], v[186:189], v[226:229], v[76:79]
	v_mfma_i32_16x16x64_i8 v[72:75], v[194:197], v[226:229], v[72:75]
	v_mfma_i32_16x16x64_i8 v[116:119], v[190:193], v[206:209], v[116:119]
	v_mfma_i32_16x16x64_i8 v[108:111], v[198:201], v[206:209], v[108:111]
	v_mfma_i32_16x16x64_i8 v[100:103], v[190:193], v[214:217], v[100:103]
	v_mfma_i32_16x16x64_i8 v[92:95], v[198:201], v[214:217], v[92:95]
	v_mfma_i32_16x16x64_i8 v[84:87], v[190:193], v[222:225], v[84:87]
	v_mfma_i32_16x16x64_i8 v[80:83], v[198:201], v[222:225], v[80:83]
	v_mfma_i32_16x16x64_i8 v[76:79], v[190:193], v[230:233], v[76:79]
	v_mfma_i32_16x16x64_i8 v[72:75], v[198:201], v[230:233], v[72:75]
	s_setprio 0
	s_barrier
	s_add_i32 s74, s57, s45
	s_mov_b32 m0, s74
	ds_read_b128 v[202:205], v180 offset:16384
	ds_read_b128 v[206:209], v180 offset:17408
	ds_read_b128 v[210:213], v180 offset:18432
	ds_read_b128 v[214:217], v180 offset:19456
	global_load_lds_dwordx4 v138, s[34:35]
	s_add_i32 m0, s74, 0x2000
	s_add_u32 s74, s34, 0x80000
	s_addc_u32 s75, s35, 0
	s_add_i32 s76, s58, s45
	global_load_lds_dwordx4 v142, s[34:35]
	s_mov_b32 m0, s76
	ds_read_b128 v[230:233], v180 offset:23552
	global_load_lds_dwordx4 v138, s[74:75]
	s_add_i32 m0, s76, 0x2000
	ds_read_b128 v[226:229], v180 offset:22528
	global_load_lds_dwordx4 v142, s[74:75]
	s_mov_b32 m0, s46
	ds_read_b128 v[222:225], v180 offset:21504
	global_load_lds_dwordx4 v136, s[36:37]
	s_mov_b32 m0, s47
	ds_read_b128 v[218:221], v180 offset:20480
	global_load_lds_dwordx4 v140, s[36:37]
	s_waitcnt vmcnt(10)
	s_waitcnt lgkmcnt(0)
	s_barrier
	s_setprio 1
	v_mfma_i32_16x16x64_i8 v[68:71], v[160:163], v[202:205], v[68:71]
	v_mfma_i32_16x16x64_i8 v[64:67], v[168:171], v[202:205], v[64:67]
	v_mfma_i32_16x16x64_i8 v[60:63], v[160:163], v[210:213], v[60:63]
	v_mfma_i32_16x16x64_i8 v[56:59], v[168:171], v[210:213], v[56:59]
	v_mfma_i32_16x16x64_i8 v[48:51], v[160:163], v[218:221], v[48:51]
	v_mfma_i32_16x16x64_i8 v[40:43], v[168:171], v[218:221], v[40:43]
	v_mfma_i32_16x16x64_i8 v[32:35], v[160:163], v[226:229], v[32:35]
	v_mfma_i32_16x16x64_i8 v[24:27], v[168:171], v[226:229], v[24:27]
	v_mfma_i32_16x16x64_i8 v[68:71], v[164:167], v[206:209], v[68:71]
	v_mfma_i32_16x16x64_i8 v[64:67], v[182:185], v[206:209], v[64:67]
	v_mfma_i32_16x16x64_i8 v[60:63], v[164:167], v[214:217], v[60:63]
	v_mfma_i32_16x16x64_i8 v[56:59], v[182:185], v[214:217], v[56:59]
	v_mfma_i32_16x16x64_i8 v[48:51], v[164:167], v[222:225], v[48:51]
	v_mfma_i32_16x16x64_i8 v[40:43], v[182:185], v[222:225], v[40:43]
	v_mfma_i32_16x16x64_i8 v[32:35], v[164:167], v[230:233], v[32:35]
	v_mfma_i32_16x16x64_i8 v[24:27], v[182:185], v[230:233], v[24:27]
	s_setprio 0
	s_setprio 1
	v_mfma_i32_16x16x64_i8 v[52:55], v[186:189], v[202:205], v[52:55]
	v_mfma_i32_16x16x64_i8 v[44:47], v[194:197], v[202:205], v[44:47]
	v_mfma_i32_16x16x64_i8 v[36:39], v[186:189], v[210:213], v[36:39]
	v_mfma_i32_16x16x64_i8 v[28:31], v[194:197], v[210:213], v[28:31]
	v_mfma_i32_16x16x64_i8 v[20:23], v[186:189], v[218:221], v[20:23]
	v_mfma_i32_16x16x64_i8 v[16:19], v[194:197], v[218:221], v[16:19]
	v_mfma_i32_16x16x64_i8 v[12:15], v[186:189], v[226:229], v[12:15]
	v_mfma_i32_16x16x64_i8 v[6:9], v[194:197], v[226:229], v[8:11]
	v_mfma_i32_16x16x64_i8 v[52:55], v[190:193], v[206:209], v[52:55]
	v_mfma_i32_16x16x64_i8 v[44:47], v[198:201], v[206:209], v[44:47]
	v_mfma_i32_16x16x64_i8 v[36:39], v[190:193], v[214:217], v[36:39]
	v_mfma_i32_16x16x64_i8 v[28:31], v[198:201], v[214:217], v[28:31]
	v_mfma_i32_16x16x64_i8 v[20:23], v[190:193], v[222:225], v[20:23]
	v_mfma_i32_16x16x64_i8 v[16:19], v[198:201], v[222:225], v[16:19]
	v_mfma_i32_16x16x64_i8 v[12:15], v[190:193], v[230:233], v[12:15]
	v_mfma_i32_16x16x64_i8 v[6:9], v[198:201], v[230:233], v[6:9]
	s_setprio 0
	s_barrier
	s_add_i32 s74, 0, 0x18000
	s_add_i32 s75, 0, 0x1c000
	ds_read_b128 v[160:163], v177 offset:32768
	ds_read_b128 v[164:167], v177 offset:33792
	ds_read_b128 v[168:171], v177 offset:34816
	ds_read_b128 v[182:185], v177 offset:35840
	ds_read_b128 v[186:189], v177 offset:49152
	ds_read_b128 v[190:193], v177 offset:50176
	ds_read_b128 v[194:197], v177 offset:51200
	ds_read_b128 v[198:201], v177 offset:52224
	s_add_u32 s36, s36, 0x80000
	s_addc_u32 s37, s37, 0
	s_mov_b32 m0, s48
	ds_read_b128 v[202:205], v180 offset:32768
	ds_read_b128 v[206:209], v180 offset:33792
	ds_read_b128 v[210:213], v180 offset:34816
	ds_read_b128 v[214:217], v180 offset:35840
	ds_read_b128 v[218:221], v180 offset:36864
	ds_read_b128 v[222:225], v180 offset:37888
	ds_read_b128 v[226:229], v180 offset:38912
	global_load_lds_dwordx4 v136, s[36:37]
	s_mov_b32 m0, s49
	ds_read_b128 v[230:233], v180 offset:39936
	global_load_lds_dwordx4 v140, s[36:37]
	s_waitcnt vmcnt(8)
	s_waitcnt lgkmcnt(0)
	s_barrier
	s_setprio 1
	v_mfma_i32_16x16x64_i8 v[132:135], v[160:163], v[202:205], v[132:135]
	v_mfma_i32_16x16x64_i8 v[128:131], v[168:171], v[202:205], v[128:131]
	v_mfma_i32_16x16x64_i8 v[124:127], v[160:163], v[210:213], v[124:127]
	v_mfma_i32_16x16x64_i8 v[120:123], v[168:171], v[210:213], v[120:123]
	v_mfma_i32_16x16x64_i8 v[112:115], v[160:163], v[218:221], v[112:115]
	v_max3_f32 v0, v0, |v152|, |v156|
	v_mfma_i32_16x16x64_i8 v[104:107], v[168:171], v[218:221], v[104:107]
	v_max3_f32 v1, v1, |v153|, |v157|
	v_mfma_i32_16x16x64_i8 v[96:99], v[160:163], v[226:229], v[96:99]
	v_max3_f32 v2, v2, |v154|, |v158|
	v_mfma_i32_16x16x64_i8 v[88:91], v[168:171], v[226:229], v[88:91]
	v_max3_f32 v3, v3, |v155|, |v159|
	v_mfma_i32_16x16x64_i8 v[132:135], v[164:167], v[206:209], v[132:135]
	v_mfma_i32_16x16x64_i8 v[128:131], v[182:185], v[206:209], v[128:131]
	v_mfma_i32_16x16x64_i8 v[124:127], v[164:167], v[214:217], v[124:127]
	v_mfma_i32_16x16x64_i8 v[120:123], v[182:185], v[214:217], v[120:123]
	v_mfma_i32_16x16x64_i8 v[112:115], v[164:167], v[222:225], v[112:115]
	v_mfma_i32_16x16x64_i8 v[104:107], v[182:185], v[222:225], v[104:107]
	v_mfma_i32_16x16x64_i8 v[96:99], v[164:167], v[230:233], v[96:99]
	v_mfma_i32_16x16x64_i8 v[88:91], v[182:185], v[230:233], v[88:91]
	s_setprio 0
	s_setprio 1
	v_mfma_i32_16x16x64_i8 v[116:119], v[186:189], v[202:205], v[116:119]
	v_mfma_i32_16x16x64_i8 v[108:111], v[194:197], v[202:205], v[108:111]
	v_mfma_i32_16x16x64_i8 v[100:103], v[186:189], v[210:213], v[100:103]
	v_mfma_i32_16x16x64_i8 v[92:95], v[194:197], v[210:213], v[92:95]
	v_mfma_i32_16x16x64_i8 v[84:87], v[186:189], v[218:221], v[84:87]
	v_mfma_i32_16x16x64_i8 v[80:83], v[194:197], v[218:221], v[80:83]
	v_mfma_i32_16x16x64_i8 v[76:79], v[186:189], v[226:229], v[76:79]
	v_mfma_i32_16x16x64_i8 v[72:75], v[194:197], v[226:229], v[72:75]
	v_mfma_i32_16x16x64_i8 v[116:119], v[190:193], v[206:209], v[116:119]
	v_mfma_i32_16x16x64_i8 v[108:111], v[198:201], v[206:209], v[108:111]
	v_mfma_i32_16x16x64_i8 v[100:103], v[190:193], v[214:217], v[100:103]
	v_mfma_i32_16x16x64_i8 v[92:95], v[198:201], v[214:217], v[92:95]
	v_mfma_i32_16x16x64_i8 v[84:87], v[190:193], v[222:225], v[84:87]
	v_mfma_i32_16x16x64_i8 v[80:83], v[198:201], v[222:225], v[80:83]
	v_mfma_i32_16x16x64_i8 v[76:79], v[190:193], v[230:233], v[76:79]
	v_mfma_i32_16x16x64_i8 v[72:75], v[198:201], v[230:233], v[72:75]
	s_setprio 0
	s_barrier
	s_add_u32 s98, s34, s14
	s_addc_u32 s99, s35, s15
	s_add_u32 s100, s36, s14
	s_addc_u32 s101, s37, s15
	s_sub_u32 s100, s100, 0x80000
	s_subb_u32 s101, s101, 0
	s_add_i32 s36, s74, s45
	s_mov_b32 m0, s36
	ds_read_b128 v[152:155], v180 offset:49152
	ds_read_b128 v[156:159], v180 offset:50176
	ds_read_b128 v[202:205], v180 offset:51200
	ds_read_b128 v[206:209], v180 offset:52224
	global_load_lds_dwordx4 v138, s[98:99]
	s_add_i32 m0, s36, 0x2000
	s_add_u32 s34, s34, 0x80080
	s_addc_u32 s35, s35, 0
	s_add_i32 s36, s75, s45
	global_load_lds_dwordx4 v142, s[98:99]
	s_mov_b32 m0, s36
	ds_read_b128 v[222:225], v180 offset:56320
	global_load_lds_dwordx4 v138, s[34:35]
	s_add_i32 m0, s36, 0x2000
	ds_read_b128 v[218:221], v180 offset:55296
	global_load_lds_dwordx4 v142, s[34:35]
	s_mov_b32 m0, s54
	ds_read_b128 v[214:217], v180 offset:54272
	global_load_lds_dwordx4 v136, s[100:101]
	s_mov_b32 m0, s55
	ds_read_b128 v[210:213], v180 offset:53248
	global_load_lds_dwordx4 v140, s[100:101]
	s_waitcnt vmcnt(8)
	s_waitcnt lgkmcnt(0)
	s_barrier
	s_setprio 1
	v_mfma_i32_16x16x64_i8 v[68:71], v[160:163], v[152:155], v[68:71]
	v_mfma_i32_16x16x64_i8 v[64:67], v[168:171], v[152:155], v[64:67]
	v_mfma_i32_16x16x64_i8 v[60:63], v[160:163], v[202:205], v[60:63]
	v_mfma_i32_16x16x64_i8 v[56:59], v[168:171], v[202:205], v[56:59]
	v_mfma_i32_16x16x64_i8 v[48:51], v[160:163], v[210:213], v[48:51]
	v_mfma_i32_16x16x64_i8 v[40:43], v[168:171], v[210:213], v[40:43]
	v_mfma_i32_16x16x64_i8 v[32:35], v[160:163], v[218:221], v[32:35]
	v_mfma_i32_16x16x64_i8 v[24:27], v[168:171], v[218:221], v[24:27]
	v_mfma_i32_16x16x64_i8 v[68:71], v[164:167], v[156:159], v[68:71]
	v_mfma_i32_16x16x64_i8 v[64:67], v[182:185], v[156:159], v[64:67]
	v_mfma_i32_16x16x64_i8 v[60:63], v[164:167], v[206:209], v[60:63]
	v_mfma_i32_16x16x64_i8 v[56:59], v[182:185], v[206:209], v[56:59]
	v_mfma_i32_16x16x64_i8 v[48:51], v[164:167], v[214:217], v[48:51]
	v_mfma_i32_16x16x64_i8 v[40:43], v[182:185], v[214:217], v[40:43]
	v_mfma_i32_16x16x64_i8 v[32:35], v[164:167], v[222:225], v[32:35]
	v_mfma_i32_16x16x64_i8 v[24:27], v[182:185], v[222:225], v[24:27]
	s_setprio 0
	s_setprio 1
	v_mfma_i32_16x16x64_i8 v[52:55], v[186:189], v[152:155], v[52:55]
	v_mfma_i32_16x16x64_i8 v[44:47], v[194:197], v[152:155], v[44:47]
	v_mfma_i32_16x16x64_i8 v[36:39], v[186:189], v[202:205], v[36:39]
	v_mfma_i32_16x16x64_i8 v[28:31], v[194:197], v[202:205], v[28:31]
	v_mfma_i32_16x16x64_i8 v[20:23], v[186:189], v[210:213], v[20:23]
	v_mfma_i32_16x16x64_i8 v[16:19], v[194:197], v[210:213], v[16:19]
	v_mfma_i32_16x16x64_i8 v[10:13], v[186:189], v[218:221], v[12:15]
	v_mfma_i32_16x16x64_i8 v[6:9], v[194:197], v[218:221], v[6:9]
	v_mfma_i32_16x16x64_i8 v[52:55], v[190:193], v[156:159], v[52:55]
	v_mfma_i32_16x16x64_i8 v[44:47], v[198:201], v[156:159], v[44:47]
	v_mfma_i32_16x16x64_i8 v[36:39], v[190:193], v[206:209], v[36:39]
	v_mfma_i32_16x16x64_i8 v[28:31], v[198:201], v[206:209], v[28:31]
	v_mfma_i32_16x16x64_i8 v[20:23], v[190:193], v[214:217], v[20:23]
	v_mfma_i32_16x16x64_i8 v[16:19], v[198:201], v[214:217], v[16:19]
	v_mfma_i32_16x16x64_i8 v[12:15], v[190:193], v[222:225], v[10:13]
	v_mfma_i32_16x16x64_i8 v[8:11], v[198:201], v[222:225], v[6:9]
	s_setprio 0
	s_barrier
	s_add_u32 s30, s30, 0x100
	s_addc_u32 s31, s31, 0
	s_add_u32 s72, s72, 0x100
	s_addc_u32 s73, s73, 0
	s_cmp_ge_i32 s8, s66
	s_cbranch_scc0 .LBB0_312

.Lp4_body:
	s_add_i32 s8, s71, 2
	s_add_u32 s28, s26, 0xfff00080
	s_addc_u32 s29, s27, -1
	s_cmp_eq_u32 s68, s71
	s_cselect_b32 s31, s64, s29
	s_cselect_b32 s30, s65, s28
	s_cselect_b32 s29, s66, s70
	s_cselect_b32 s28, s67, s69
	ds_read_b128 v[172:175], v163
	ds_read_b128 v[176:179], v163 offset:1024
	ds_read_b128 v[180:183], v163 offset:2048
	ds_read_b128 v[184:187], v163 offset:3072
	ds_read_b128 v[188:191], v163 offset:16384
	ds_read_b128 v[192:195], v163 offset:17408
	ds_read_b128 v[196:199], v163 offset:18432
	ds_read_b128 v[200:203], v163 offset:19456
	s_add_i32 m0, s43, 0xc000
	ds_read_b128 v[204:207], v166
	ds_read_b128 v[208:211], v166 offset:1024
	ds_read_b128 v[212:215], v166 offset:2048
	ds_read_b128 v[216:219], v166 offset:3072
	ds_read_b128 v[220:223], v166 offset:4096
	ds_read_b128 v[224:227], v166 offset:5120
	ds_read_b128 v[236:239], v166 offset:6144
	global_load_lds_dwordx4 v146, s[26:27]
	s_add_i32 m0, s43, 0xe000
	ds_read_b128 v[240:243], v166 offset:7168
	global_load_lds_dwordx4 v148, s[26:27]
	s_waitcnt vmcnt(8)
	s_waitcnt lgkmcnt(0)
	s_barrier
	s_setprio 1
	v_mfma_f32_16x16x32_bf16 v[132:135], v[172:175], v[204:207], v[132:135]
	v_mfma_f32_16x16x32_bf16 v[128:131], v[180:183], v[204:207], v[128:131]
	v_mfma_f32_16x16x32_bf16 v[116:119], v[172:175], v[212:215], v[116:119]
	v_mfma_f32_16x16x32_bf16 v[112:115], v[180:183], v[212:215], v[112:115]
	v_mfma_f32_16x16x32_bf16 v[100:103], v[172:175], v[220:223], v[100:103]
	v_mfma_f32_16x16x32_bf16 v[96:99], v[180:183], v[220:223], v[96:99]
	v_mfma_f32_16x16x32_bf16 v[84:87], v[172:175], v[236:239], v[84:87]
	v_mfma_f32_16x16x32_bf16 v[80:83], v[180:183], v[236:239], v[80:83]
	v_mfma_f32_16x16x32_bf16 v[132:135], v[176:179], v[208:211], v[132:135]
	v_mfma_f32_16x16x32_bf16 v[128:131], v[184:187], v[208:211], v[128:131]
	v_mfma_f32_16x16x32_bf16 v[116:119], v[176:179], v[216:219], v[116:119]
	v_mfma_f32_16x16x32_bf16 v[112:115], v[184:187], v[216:219], v[112:115]
	v_mfma_f32_16x16x32_bf16 v[100:103], v[176:179], v[224:227], v[100:103]
	v_mfma_f32_16x16x32_bf16 v[96:99], v[184:187], v[224:227], v[96:99]
	v_mfma_f32_16x16x32_bf16 v[84:87], v[176:179], v[240:243], v[84:87]
	v_mfma_f32_16x16x32_bf16 v[80:83], v[184:187], v[240:243], v[80:83]
	s_setprio 0
	s_setprio 1
	v_mfma_f32_16x16x32_bf16 v[124:127], v[188:191], v[204:207], v[124:127]
	v_mfma_f32_16x16x32_bf16 v[120:123], v[196:199], v[204:207], v[120:123]
	v_mfma_f32_16x16x32_bf16 v[108:111], v[188:191], v[212:215], v[108:111]
	v_mfma_f32_16x16x32_bf16 v[104:107], v[196:199], v[212:215], v[104:107]
	v_mfma_f32_16x16x32_bf16 v[92:95], v[188:191], v[220:223], v[92:95]
	v_mfma_f32_16x16x32_bf16 v[88:91], v[196:199], v[220:223], v[88:91]
	v_mfma_f32_16x16x32_bf16 v[76:79], v[188:191], v[236:239], v[76:79]
	v_mfma_f32_16x16x32_bf16 v[72:75], v[196:199], v[236:239], v[72:75]
	v_mfma_f32_16x16x32_bf16 v[124:127], v[192:195], v[208:211], v[124:127]
	v_mfma_f32_16x16x32_bf16 v[120:123], v[200:203], v[208:211], v[120:123]
	v_mfma_f32_16x16x32_bf16 v[108:111], v[192:195], v[216:219], v[108:111]
	v_mfma_f32_16x16x32_bf16 v[104:107], v[200:203], v[216:219], v[104:107]
	v_mfma_f32_16x16x32_bf16 v[92:95], v[192:195], v[224:227], v[92:95]
	v_mfma_f32_16x16x32_bf16 v[88:91], v[200:203], v[224:227], v[88:91]
	v_mfma_f32_16x16x32_bf16 v[76:79], v[192:195], v[240:243], v[76:79]
	v_mfma_f32_16x16x32_bf16 v[72:75], v[200:203], v[240:243], v[72:75]
	s_setprio 0
	s_barrier
	s_add_i32 s71, s53, s40
	s_mov_b32 m0, s71
	ds_read_b128 v[204:207], v166 offset:16384
	ds_read_b128 v[208:211], v166 offset:17408
	ds_read_b128 v[212:215], v166 offset:18432
	ds_read_b128 v[216:219], v166 offset:19456
	global_load_lds_dwordx4 v138, s[28:29]
	s_add_i32 m0, s71, 0x2000
	s_add_u32 s72, s28, 0x100000
	s_addc_u32 s73, s29, 0
	s_add_i32 s71, s54, s40
	global_load_lds_dwordx4 v142, s[28:29]
	s_mov_b32 m0, s71
	ds_read_b128 v[240:243], v166 offset:23552
	global_load_lds_dwordx4 v138, s[72:73]
	s_add_i32 m0, s71, 0x2000
	ds_read_b128 v[236:239], v166 offset:22528
	global_load_lds_dwordx4 v142, s[72:73]
	s_mov_b32 m0, s43
	ds_read_b128 v[224:227], v166 offset:21504
	global_load_lds_dwordx4 v136, s[30:31]
	s_mov_b32 m0, s44
	ds_read_b128 v[220:223], v166 offset:20480
	global_load_lds_dwordx4 v140, s[30:31]
	s_waitcnt vmcnt(8)
	s_waitcnt lgkmcnt(0)
	s_barrier
	s_setprio 1
	v_mfma_f32_16x16x32_bf16 v[68:71], v[172:175], v[204:207], v[68:71]
	v_mfma_f32_16x16x32_bf16 v[64:67], v[180:183], v[204:207], v[64:67]
	v_mfma_f32_16x16x32_bf16 v[52:55], v[172:175], v[212:215], v[52:55]
	v_mfma_f32_16x16x32_bf16 v[48:51], v[180:183], v[212:215], v[48:51]
	v_mfma_f32_16x16x32_bf16 v[36:39], v[172:175], v[220:223], v[36:39]
	v_mfma_f32_16x16x32_bf16 v[32:35], v[180:183], v[220:223], v[32:35]
	v_mfma_f32_16x16x32_bf16 v[20:23], v[172:175], v[236:239], v[20:23]
	v_mfma_f32_16x16x32_bf16 v[16:19], v[180:183], v[236:239], v[16:19]
	v_mfma_f32_16x16x32_bf16 v[68:71], v[176:179], v[208:211], v[68:71]
	v_mfma_f32_16x16x32_bf16 v[64:67], v[184:187], v[208:211], v[64:67]
	v_mfma_f32_16x16x32_bf16 v[52:55], v[176:179], v[216:219], v[52:55]
	v_mfma_f32_16x16x32_bf16 v[48:51], v[184:187], v[216:219], v[48:51]
	v_mfma_f32_16x16x32_bf16 v[36:39], v[176:179], v[224:227], v[36:39]
	v_mfma_f32_16x16x32_bf16 v[32:35], v[184:187], v[224:227], v[32:35]
	v_mfma_f32_16x16x32_bf16 v[20:23], v[176:179], v[240:243], v[20:23]
	v_mfma_f32_16x16x32_bf16 v[16:19], v[184:187], v[240:243], v[16:19]
	s_setprio 0
	s_setprio 1
	v_mfma_f32_16x16x32_bf16 v[60:63], v[188:191], v[204:207], v[60:63]
	v_mfma_f32_16x16x32_bf16 v[56:59], v[196:199], v[204:207], v[56:59]
	v_mfma_f32_16x16x32_bf16 v[44:47], v[188:191], v[212:215], v[44:47]
	v_mfma_f32_16x16x32_bf16 v[40:43], v[196:199], v[212:215], v[40:43]
	v_mfma_f32_16x16x32_bf16 v[28:31], v[188:191], v[220:223], v[28:31]
	v_mfma_f32_16x16x32_bf16 v[24:27], v[196:199], v[220:223], v[24:27]
	v_mfma_f32_16x16x32_bf16 v[12:15], v[188:191], v[236:239], v[12:15]
	v_mfma_f32_16x16x32_bf16 v[6:9], v[196:199], v[236:239], v[8:11]
	v_mfma_f32_16x16x32_bf16 v[60:63], v[192:195], v[208:211], v[60:63]
	v_mfma_f32_16x16x32_bf16 v[56:59], v[200:203], v[208:211], v[56:59]
	v_mfma_f32_16x16x32_bf16 v[44:47], v[192:195], v[216:219], v[44:47]
	v_mfma_f32_16x16x32_bf16 v[40:43], v[200:203], v[216:219], v[40:43]
	v_mfma_f32_16x16x32_bf16 v[28:31], v[192:195], v[224:227], v[28:31]
	v_mfma_f32_16x16x32_bf16 v[24:27], v[200:203], v[224:227], v[24:27]
	v_mfma_f32_16x16x32_bf16 v[12:15], v[192:195], v[240:243], v[12:15]
	v_mfma_f32_16x16x32_bf16 v[6:9], v[200:203], v[240:243], v[6:9]
	s_setprio 0
	s_barrier
	s_add_i32 s71, 0, 0x18000
	s_add_i32 s72, 0, 0x1c000
	ds_read_b128 v[172:175], v163 offset:32768
	ds_read_b128 v[176:179], v163 offset:33792
	ds_read_b128 v[180:183], v163 offset:34816
	ds_read_b128 v[184:187], v163 offset:35840
	ds_read_b128 v[188:191], v163 offset:49152
	ds_read_b128 v[192:195], v163 offset:50176
	ds_read_b128 v[196:199], v163 offset:51200
	ds_read_b128 v[200:203], v163 offset:52224
	s_add_u32 s30, s30, 0x100000
	s_addc_u32 s31, s31, 0
	s_mov_b32 m0, s45
	ds_read_b128 v[204:207], v166 offset:32768
	ds_read_b128 v[208:211], v166 offset:33792
	ds_read_b128 v[212:215], v166 offset:34816
	ds_read_b128 v[216:219], v166 offset:35840
	ds_read_b128 v[220:223], v166 offset:36864
	ds_read_b128 v[224:227], v166 offset:37888
	ds_read_b128 v[236:239], v166 offset:38912
	global_load_lds_dwordx4 v136, s[30:31]
	s_mov_b32 m0, s46
	ds_read_b128 v[240:243], v166 offset:39936
	global_load_lds_dwordx4 v140, s[30:31]
	s_waitcnt vmcnt(8)
	s_waitcnt lgkmcnt(0)
	s_barrier
	s_setprio 1
	v_mfma_f32_16x16x32_bf16 v[132:135], v[172:175], v[204:207], v[132:135]
	v_mfma_f32_16x16x32_bf16 v[128:131], v[180:183], v[204:207], v[128:131]
	v_mfma_f32_16x16x32_bf16 v[116:119], v[172:175], v[212:215], v[116:119]
	v_mfma_f32_16x16x32_bf16 v[112:115], v[180:183], v[212:215], v[112:115]
	v_mfma_f32_16x16x32_bf16 v[100:103], v[172:175], v[220:223], v[100:103]
	v_mfma_f32_16x16x32_bf16 v[96:99], v[180:183], v[220:223], v[96:99]
	v_mfma_f32_16x16x32_bf16 v[84:87], v[172:175], v[236:239], v[84:87]
	v_mfma_f32_16x16x32_bf16 v[80:83], v[180:183], v[236:239], v[80:83]
	v_mfma_f32_16x16x32_bf16 v[132:135], v[176:179], v[208:211], v[132:135]
	v_mfma_f32_16x16x32_bf16 v[128:131], v[184:187], v[208:211], v[128:131]
	v_mfma_f32_16x16x32_bf16 v[116:119], v[176:179], v[216:219], v[116:119]
	v_mfma_f32_16x16x32_bf16 v[112:115], v[184:187], v[216:219], v[112:115]
	v_mfma_f32_16x16x32_bf16 v[100:103], v[176:179], v[224:227], v[100:103]
	v_mfma_f32_16x16x32_bf16 v[96:99], v[184:187], v[224:227], v[96:99]
	v_mfma_f32_16x16x32_bf16 v[84:87], v[176:179], v[240:243], v[84:87]
	v_mfma_f32_16x16x32_bf16 v[80:83], v[184:187], v[240:243], v[80:83]
	s_setprio 0
	s_setprio 1
	v_mfma_f32_16x16x32_bf16 v[124:127], v[188:191], v[204:207], v[124:127]
	v_mfma_f32_16x16x32_bf16 v[120:123], v[196:199], v[204:207], v[120:123]
	v_mfma_f32_16x16x32_bf16 v[108:111], v[188:191], v[212:215], v[108:111]
	v_mfma_f32_16x16x32_bf16 v[104:107], v[196:199], v[212:215], v[104:107]
	v_mfma_f32_16x16x32_bf16 v[92:95], v[188:191], v[220:223], v[92:95]
	v_mfma_f32_16x16x32_bf16 v[88:91], v[196:199], v[220:223], v[88:91]
	v_mfma_f32_16x16x32_bf16 v[76:79], v[188:191], v[236:239], v[76:79]
	v_mfma_f32_16x16x32_bf16 v[72:75], v[196:199], v[236:239], v[72:75]
	v_mfma_f32_16x16x32_bf16 v[124:127], v[192:195], v[208:211], v[124:127]
	v_mfma_f32_16x16x32_bf16 v[120:123], v[200:203], v[208:211], v[120:123]
	v_mfma_f32_16x16x32_bf16 v[108:111], v[192:195], v[216:219], v[108:111]
	v_mfma_f32_16x16x32_bf16 v[104:107], v[200:203], v[216:219], v[104:107]
	v_mfma_f32_16x16x32_bf16 v[92:95], v[192:195], v[224:227], v[92:95]
	v_mfma_f32_16x16x32_bf16 v[88:91], v[200:203], v[224:227], v[88:91]
	v_mfma_f32_16x16x32_bf16 v[76:79], v[192:195], v[240:243], v[76:79]
	v_mfma_f32_16x16x32_bf16 v[72:75], v[200:203], v[240:243], v[72:75]
	s_setprio 0
	s_barrier
	s_add_u32 s74, s28, s6
	s_addc_u32 s75, s29, s7
	s_add_u32 s76, s30, s6
	s_addc_u32 s77, s31, s7
	s_sub_u32 s76, s76, 0x100000
	s_subb_u32 s77, s77, 0
	s_add_i32 s30, s71, s40
	s_mov_b32 m0, s30
	ds_read_b128 v[152:155], v166 offset:49152
	ds_read_b128 v[168:171], v166 offset:50176
	ds_read_b128 v[204:207], v166 offset:51200
	ds_read_b128 v[208:211], v166 offset:52224
	global_load_lds_dwordx4 v138, s[74:75]
	s_add_i32 m0, s30, 0x2000
	s_add_u32 s28, s28, 0x100080
	s_addc_u32 s29, s29, 0
	s_add_i32 s30, s72, s40
	global_load_lds_dwordx4 v142, s[74:75]
	s_mov_b32 m0, s30
	ds_read_b128 v[224:227], v166 offset:56320
	global_load_lds_dwordx4 v138, s[28:29]
	s_add_i32 m0, s30, 0x2000
	ds_read_b128 v[220:223], v166 offset:55296
	global_load_lds_dwordx4 v142, s[28:29]
	s_mov_b32 m0, s49
	ds_read_b128 v[216:219], v166 offset:54272
	global_load_lds_dwordx4 v136, s[76:77]
	s_mov_b32 m0, s50
	ds_read_b128 v[212:215], v166 offset:53248
	global_load_lds_dwordx4 v140, s[76:77]
	s_waitcnt vmcnt(8)
	s_waitcnt lgkmcnt(0)
	s_barrier
	s_setprio 1
	v_mfma_f32_16x16x32_bf16 v[68:71], v[172:175], v[152:155], v[68:71]
	v_mfma_f32_16x16x32_bf16 v[64:67], v[180:183], v[152:155], v[64:67]
	v_mfma_f32_16x16x32_bf16 v[52:55], v[172:175], v[204:207], v[52:55]
	v_mfma_f32_16x16x32_bf16 v[48:51], v[180:183], v[204:207], v[48:51]
	v_mfma_f32_16x16x32_bf16 v[36:39], v[172:175], v[212:215], v[36:39]
	v_mfma_f32_16x16x32_bf16 v[32:35], v[180:183], v[212:215], v[32:35]
	v_mfma_f32_16x16x32_bf16 v[20:23], v[172:175], v[220:223], v[20:23]
	v_mfma_f32_16x16x32_bf16 v[16:19], v[180:183], v[220:223], v[16:19]
	v_mfma_f32_16x16x32_bf16 v[68:71], v[176:179], v[168:171], v[68:71]
	v_mfma_f32_16x16x32_bf16 v[64:67], v[184:187], v[168:171], v[64:67]
	v_mfma_f32_16x16x32_bf16 v[52:55], v[176:179], v[208:211], v[52:55]
	v_mfma_f32_16x16x32_bf16 v[48:51], v[184:187], v[208:211], v[48:51]
	v_mfma_f32_16x16x32_bf16 v[36:39], v[176:179], v[216:219], v[36:39]
	v_mfma_f32_16x16x32_bf16 v[32:35], v[184:187], v[216:219], v[32:35]
	v_mfma_f32_16x16x32_bf16 v[20:23], v[176:179], v[224:227], v[20:23]
	v_mfma_f32_16x16x32_bf16 v[16:19], v[184:187], v[224:227], v[16:19]
	s_setprio 0
	s_setprio 1
	v_mfma_f32_16x16x32_bf16 v[60:63], v[188:191], v[152:155], v[60:63]
	v_mfma_f32_16x16x32_bf16 v[56:59], v[196:199], v[152:155], v[56:59]
	v_mfma_f32_16x16x32_bf16 v[44:47], v[188:191], v[204:207], v[44:47]
	v_mfma_f32_16x16x32_bf16 v[40:43], v[196:199], v[204:207], v[40:43]
	v_mfma_f32_16x16x32_bf16 v[28:31], v[188:191], v[212:215], v[28:31]
	v_mfma_f32_16x16x32_bf16 v[24:27], v[196:199], v[212:215], v[24:27]
	v_mfma_f32_16x16x32_bf16 v[10:13], v[188:191], v[220:223], v[12:15]
	v_mfma_f32_16x16x32_bf16 v[6:9], v[196:199], v[220:223], v[6:9]
	v_mfma_f32_16x16x32_bf16 v[60:63], v[192:195], v[168:171], v[60:63]
	v_mfma_f32_16x16x32_bf16 v[56:59], v[200:203], v[168:171], v[56:59]
	v_mfma_f32_16x16x32_bf16 v[44:47], v[192:195], v[208:211], v[44:47]
	v_mfma_f32_16x16x32_bf16 v[40:43], v[200:203], v[208:211], v[40:43]
	v_mfma_f32_16x16x32_bf16 v[28:31], v[192:195], v[216:219], v[28:31]
	v_mfma_f32_16x16x32_bf16 v[24:27], v[200:203], v[216:219], v[24:27]
	v_mfma_f32_16x16x32_bf16 v[12:15], v[192:195], v[224:227], v[10:13]
	v_mfma_f32_16x16x32_bf16 v[8:11], v[200:203], v[224:227], v[6:9]
	s_setprio 0
	s_barrier
	s_add_u32 s26, s26, 0x100
	s_addc_u32 s27, s27, 0
	s_add_u32 s69, s69, 0x100
	s_addc_u32 s70, s70, 0
	s_cmp_ge_i32 s8, s63
	s_cbranch_scc0 .Lp4_top
	s_branch .Lp4_epi

.LBB0_1033:
	s_add_i32 s8, s71, 2
	s_add_u32 s28, s26, 0xfff00080
	s_addc_u32 s29, s27, -1
	s_cmp_eq_u32 s68, s71
	s_cselect_b32 s31, s64, s29
	s_cselect_b32 s30, s65, s28
	s_cselect_b32 s29, s66, s70
	s_cselect_b32 s28, s67, s69
	s_cmpk_lt_i32 s3, 0x56
	s_cselect_b32 s71, s52, 0x2b00
	s_mov_b32 s72, 0xac00
	s_cselect_b32 s74, s72, 0x4000
	s_sub_i32 s71, s71, s33
	v_min3_i32 v5, s71, v160, 2
	v_sub_u32_e32 v160, v160, v5
	v_readfirstlane_b32 s71, v5
	s_max_i32 s72, s71, 0
	s_add_i32 s72, s33, s72
	s_add_i32 s75, s72, -1
	s_min_i32 s72, s33, s75
	s_mul_hi_i32 s73, s74, s72
	s_mul_i32 s72, s74, s72
	s_add_u32 s72, s34, s72
	s_addc_u32 s73, s35, s73
	s_mul_hi_i32 s76, s74, s75
	s_mul_i32 s74, s74, s75
	s_add_u32 s74, s34, s74
	global_load_dwordx4 v[152:155], v159, s[72:73] nt
	s_addc_u32 s75, s35, s76
	global_load_dwordx4 v[168:171], v159, s[74:75] nt
	s_add_i32 s33, s71, s33
	ds_read_b128 v[172:175], v163
	ds_read_b128 v[176:179], v163 offset:1024
	ds_read_b128 v[180:183], v163 offset:2048
	ds_read_b128 v[184:187], v163 offset:3072
	ds_read_b128 v[188:191], v163 offset:16384
	ds_read_b128 v[192:195], v163 offset:17408
	ds_read_b128 v[196:199], v163 offset:18432
	ds_read_b128 v[200:203], v163 offset:19456
	s_add_i32 m0, s43, 0xc000
	ds_read_b128 v[204:207], v166
	ds_read_b128 v[208:211], v166 offset:1024
	ds_read_b128 v[212:215], v166 offset:2048
	ds_read_b128 v[216:219], v166 offset:3072
	ds_read_b128 v[220:223], v166 offset:4096
	ds_read_b128 v[224:227], v166 offset:5120
	ds_read_b128 v[236:239], v166 offset:6144
	global_load_lds_dwordx4 v146, s[26:27]
	s_add_i32 m0, s43, 0xe000
	ds_read_b128 v[240:243], v166 offset:7168
	global_load_lds_dwordx4 v148, s[26:27]
	s_waitcnt vmcnt(10)
	s_waitcnt lgkmcnt(0)
	s_barrier
	s_setprio 1
	v_mfma_f32_16x16x32_bf16 v[132:135], v[172:175], v[204:207], v[132:135]
	v_mfma_f32_16x16x32_bf16 v[128:131], v[180:183], v[204:207], v[128:131]
	v_mfma_f32_16x16x32_bf16 v[116:119], v[172:175], v[212:215], v[116:119]
	v_mfma_f32_16x16x32_bf16 v[112:115], v[180:183], v[212:215], v[112:115]
	v_mfma_f32_16x16x32_bf16 v[100:103], v[172:175], v[220:223], v[100:103]
	v_mfma_f32_16x16x32_bf16 v[96:99], v[180:183], v[220:223], v[96:99]
	v_mfma_f32_16x16x32_bf16 v[84:87], v[172:175], v[236:239], v[84:87]
	v_mfma_f32_16x16x32_bf16 v[80:83], v[180:183], v[236:239], v[80:83]
	v_mfma_f32_16x16x32_bf16 v[132:135], v[176:179], v[208:211], v[132:135]
	v_mfma_f32_16x16x32_bf16 v[128:131], v[184:187], v[208:211], v[128:131]
	v_mfma_f32_16x16x32_bf16 v[116:119], v[176:179], v[216:219], v[116:119]
	v_mfma_f32_16x16x32_bf16 v[112:115], v[184:187], v[216:219], v[112:115]
	v_mfma_f32_16x16x32_bf16 v[100:103], v[176:179], v[224:227], v[100:103]
	v_mfma_f32_16x16x32_bf16 v[96:99], v[184:187], v[224:227], v[96:99]
	v_mfma_f32_16x16x32_bf16 v[84:87], v[176:179], v[240:243], v[84:87]
	v_mfma_f32_16x16x32_bf16 v[80:83], v[184:187], v[240:243], v[80:83]
	s_setprio 0
	s_setprio 1
	v_mfma_f32_16x16x32_bf16 v[124:127], v[188:191], v[204:207], v[124:127]
	v_mfma_f32_16x16x32_bf16 v[120:123], v[196:199], v[204:207], v[120:123]
	v_mfma_f32_16x16x32_bf16 v[108:111], v[188:191], v[212:215], v[108:111]
	v_mfma_f32_16x16x32_bf16 v[104:107], v[196:199], v[212:215], v[104:107]
	v_mfma_f32_16x16x32_bf16 v[92:95], v[188:191], v[220:223], v[92:95]
	v_mfma_f32_16x16x32_bf16 v[88:91], v[196:199], v[220:223], v[88:91]
	v_mfma_f32_16x16x32_bf16 v[76:79], v[188:191], v[236:239], v[76:79]
	v_mfma_f32_16x16x32_bf16 v[72:75], v[196:199], v[236:239], v[72:75]
	v_mfma_f32_16x16x32_bf16 v[124:127], v[192:195], v[208:211], v[124:127]
	v_mfma_f32_16x16x32_bf16 v[120:123], v[200:203], v[208:211], v[120:123]
	v_mfma_f32_16x16x32_bf16 v[108:111], v[192:195], v[216:219], v[108:111]
	v_mfma_f32_16x16x32_bf16 v[104:107], v[200:203], v[216:219], v[104:107]
	v_mfma_f32_16x16x32_bf16 v[92:95], v[192:195], v[224:227], v[92:95]
	v_mfma_f32_16x16x32_bf16 v[88:91], v[200:203], v[224:227], v[88:91]
	v_mfma_f32_16x16x32_bf16 v[76:79], v[192:195], v[240:243], v[76:79]
	v_mfma_f32_16x16x32_bf16 v[72:75], v[200:203], v[240:243], v[72:75]
	s_setprio 0
	s_barrier
	s_add_i32 s71, s53, s40
	s_mov_b32 m0, s71
	ds_read_b128 v[204:207], v166 offset:16384
	ds_read_b128 v[208:211], v166 offset:17408
	ds_read_b128 v[212:215], v166 offset:18432
	ds_read_b128 v[216:219], v166 offset:19456
	global_load_lds_dwordx4 v138, s[28:29]
	s_add_i32 m0, s71, 0x2000
	s_add_u32 s72, s28, 0x100000
	s_addc_u32 s73, s29, 0
	s_add_i32 s71, s54, s40
	global_load_lds_dwordx4 v142, s[28:29]
	s_mov_b32 m0, s71
	ds_read_b128 v[240:243], v166 offset:23552
	global_load_lds_dwordx4 v138, s[72:73]
	s_add_i32 m0, s71, 0x2000
	ds_read_b128 v[236:239], v166 offset:22528
	global_load_lds_dwordx4 v142, s[72:73]
	s_mov_b32 m0, s43
	ds_read_b128 v[224:227], v166 offset:21504
	global_load_lds_dwordx4 v136, s[30:31]
	s_mov_b32 m0, s44
	ds_read_b128 v[220:223], v166 offset:20480
	global_load_lds_dwordx4 v140, s[30:31]
	s_waitcnt vmcnt(10)
	s_waitcnt lgkmcnt(0)
	s_barrier
	s_setprio 1
	v_mfma_f32_16x16x32_bf16 v[68:71], v[172:175], v[204:207], v[68:71]
	v_mfma_f32_16x16x32_bf16 v[64:67], v[180:183], v[204:207], v[64:67]
	v_mfma_f32_16x16x32_bf16 v[52:55], v[172:175], v[212:215], v[52:55]
	v_mfma_f32_16x16x32_bf16 v[48:51], v[180:183], v[212:215], v[48:51]
	v_mfma_f32_16x16x32_bf16 v[36:39], v[172:175], v[220:223], v[36:39]
	v_mfma_f32_16x16x32_bf16 v[32:35], v[180:183], v[220:223], v[32:35]
	v_mfma_f32_16x16x32_bf16 v[20:23], v[172:175], v[236:239], v[20:23]
	v_mfma_f32_16x16x32_bf16 v[16:19], v[180:183], v[236:239], v[16:19]
	v_mfma_f32_16x16x32_bf16 v[68:71], v[176:179], v[208:211], v[68:71]
	v_mfma_f32_16x16x32_bf16 v[64:67], v[184:187], v[208:211], v[64:67]
	v_mfma_f32_16x16x32_bf16 v[52:55], v[176:179], v[216:219], v[52:55]
	v_mfma_f32_16x16x32_bf16 v[48:51], v[184:187], v[216:219], v[48:51]
	v_mfma_f32_16x16x32_bf16 v[36:39], v[176:179], v[224:227], v[36:39]
	v_mfma_f32_16x16x32_bf16 v[32:35], v[184:187], v[224:227], v[32:35]
	v_mfma_f32_16x16x32_bf16 v[20:23], v[176:179], v[240:243], v[20:23]
	v_mfma_f32_16x16x32_bf16 v[16:19], v[184:187], v[240:243], v[16:19]
	s_setprio 0
	s_setprio 1
	v_mfma_f32_16x16x32_bf16 v[60:63], v[188:191], v[204:207], v[60:63]
	v_mfma_f32_16x16x32_bf16 v[56:59], v[196:199], v[204:207], v[56:59]
	v_mfma_f32_16x16x32_bf16 v[44:47], v[188:191], v[212:215], v[44:47]
	v_mfma_f32_16x16x32_bf16 v[40:43], v[196:199], v[212:215], v[40:43]
	v_mfma_f32_16x16x32_bf16 v[28:31], v[188:191], v[220:223], v[28:31]
	v_mfma_f32_16x16x32_bf16 v[24:27], v[196:199], v[220:223], v[24:27]
	v_mfma_f32_16x16x32_bf16 v[12:15], v[188:191], v[236:239], v[12:15]
	v_mfma_f32_16x16x32_bf16 v[6:9], v[196:199], v[236:239], v[8:11]
	v_mfma_f32_16x16x32_bf16 v[60:63], v[192:195], v[208:211], v[60:63]
	v_mfma_f32_16x16x32_bf16 v[56:59], v[200:203], v[208:211], v[56:59]
	v_mfma_f32_16x16x32_bf16 v[44:47], v[192:195], v[216:219], v[44:47]
	v_mfma_f32_16x16x32_bf16 v[40:43], v[200:203], v[216:219], v[40:43]
	v_mfma_f32_16x16x32_bf16 v[28:31], v[192:195], v[224:227], v[28:31]
	v_mfma_f32_16x16x32_bf16 v[24:27], v[200:203], v[224:227], v[24:27]
	v_mfma_f32_16x16x32_bf16 v[12:15], v[192:195], v[240:243], v[12:15]
	v_mfma_f32_16x16x32_bf16 v[6:9], v[200:203], v[240:243], v[6:9]
	s_setprio 0
	s_barrier
	s_add_i32 s71, 0, 0x18000
	s_add_i32 s72, 0, 0x1c000
	ds_read_b128 v[172:175], v163 offset:32768
	ds_read_b128 v[176:179], v163 offset:33792
	ds_read_b128 v[180:183], v163 offset:34816
	ds_read_b128 v[184:187], v163 offset:35840
	ds_read_b128 v[188:191], v163 offset:49152
	ds_read_b128 v[192:195], v163 offset:50176
	ds_read_b128 v[196:199], v163 offset:51200
	ds_read_b128 v[200:203], v163 offset:52224
	s_add_u32 s30, s30, 0x100000
	s_addc_u32 s31, s31, 0
	s_mov_b32 m0, s45
	ds_read_b128 v[204:207], v166 offset:32768
	ds_read_b128 v[208:211], v166 offset:33792
	ds_read_b128 v[212:215], v166 offset:34816
	ds_read_b128 v[216:219], v166 offset:35840
	ds_read_b128 v[220:223], v166 offset:36864
	ds_read_b128 v[224:227], v166 offset:37888
	ds_read_b128 v[236:239], v166 offset:38912
	global_load_lds_dwordx4 v136, s[30:31]
	s_mov_b32 m0, s46
	ds_read_b128 v[240:243], v166 offset:39936
	global_load_lds_dwordx4 v140, s[30:31]
	s_waitcnt vmcnt(8)
	s_waitcnt lgkmcnt(0)
	s_barrier
	s_setprio 1
	v_mfma_f32_16x16x32_bf16 v[132:135], v[172:175], v[204:207], v[132:135]
	v_mfma_f32_16x16x32_bf16 v[128:131], v[180:183], v[204:207], v[128:131]
	v_mfma_f32_16x16x32_bf16 v[116:119], v[172:175], v[212:215], v[116:119]
	v_mfma_f32_16x16x32_bf16 v[112:115], v[180:183], v[212:215], v[112:115]
	v_mfma_f32_16x16x32_bf16 v[100:103], v[172:175], v[220:223], v[100:103]
	v_max3_f32 v0, v0, |v152|, |v168|
	v_mfma_f32_16x16x32_bf16 v[96:99], v[180:183], v[220:223], v[96:99]
	v_max3_f32 v1, v1, |v153|, |v169|
	v_mfma_f32_16x16x32_bf16 v[84:87], v[172:175], v[236:239], v[84:87]
	v_max3_f32 v2, v2, |v154|, |v170|
	v_mfma_f32_16x16x32_bf16 v[80:83], v[180:183], v[236:239], v[80:83]
	v_max3_f32 v3, v3, |v155|, |v171|
	v_mfma_f32_16x16x32_bf16 v[132:135], v[176:179], v[208:211], v[132:135]
	v_mfma_f32_16x16x32_bf16 v[128:131], v[184:187], v[208:211], v[128:131]
	v_mfma_f32_16x16x32_bf16 v[116:119], v[176:179], v[216:219], v[116:119]
	v_mfma_f32_16x16x32_bf16 v[112:115], v[184:187], v[216:219], v[112:115]
	v_mfma_f32_16x16x32_bf16 v[100:103], v[176:179], v[224:227], v[100:103]
	v_mfma_f32_16x16x32_bf16 v[96:99], v[184:187], v[224:227], v[96:99]
	v_mfma_f32_16x16x32_bf16 v[84:87], v[176:179], v[240:243], v[84:87]
	v_mfma_f32_16x16x32_bf16 v[80:83], v[184:187], v[240:243], v[80:83]
	s_setprio 0
	s_setprio 1
	v_mfma_f32_16x16x32_bf16 v[124:127], v[188:191], v[204:207], v[124:127]
	v_mfma_f32_16x16x32_bf16 v[120:123], v[196:199], v[204:207], v[120:123]
	v_mfma_f32_16x16x32_bf16 v[108:111], v[188:191], v[212:215], v[108:111]
	v_mfma_f32_16x16x32_bf16 v[104:107], v[196:199], v[212:215], v[104:107]
	v_mfma_f32_16x16x32_bf16 v[92:95], v[188:191], v[220:223], v[92:95]
	v_mfma_f32_16x16x32_bf16 v[88:91], v[196:199], v[220:223], v[88:91]
	v_mfma_f32_16x16x32_bf16 v[76:79], v[188:191], v[236:239], v[76:79]
	v_mfma_f32_16x16x32_bf16 v[72:75], v[196:199], v[236:239], v[72:75]
	v_mfma_f32_16x16x32_bf16 v[124:127], v[192:195], v[208:211], v[124:127]
	v_mfma_f32_16x16x32_bf16 v[120:123], v[200:203], v[208:211], v[120:123]
	v_mfma_f32_16x16x32_bf16 v[108:111], v[192:195], v[216:219], v[108:111]
	v_mfma_f32_16x16x32_bf16 v[104:107], v[200:203], v[216:219], v[104:107]
	v_mfma_f32_16x16x32_bf16 v[92:95], v[192:195], v[224:227], v[92:95]
	v_mfma_f32_16x16x32_bf16 v[88:91], v[200:203], v[224:227], v[88:91]
	v_mfma_f32_16x16x32_bf16 v[76:79], v[192:195], v[240:243], v[76:79]
	v_mfma_f32_16x16x32_bf16 v[72:75], v[200:203], v[240:243], v[72:75]
	s_setprio 0
	s_barrier
	s_add_u32 s74, s28, s6
	s_addc_u32 s75, s29, s7
	s_add_u32 s76, s30, s6
	s_addc_u32 s77, s31, s7
	s_sub_u32 s76, s76, 0x100000
	s_subb_u32 s77, s77, 0
	s_add_i32 s30, s71, s40
	s_mov_b32 m0, s30
	ds_read_b128 v[152:155], v166 offset:49152
	ds_read_b128 v[168:171], v166 offset:50176
	ds_read_b128 v[204:207], v166 offset:51200
	ds_read_b128 v[208:211], v166 offset:52224
	global_load_lds_dwordx4 v138, s[74:75]
	s_add_i32 m0, s30, 0x2000
	s_add_u32 s28, s28, 0x100080
	s_addc_u32 s29, s29, 0
	s_add_i32 s30, s72, s40
	global_load_lds_dwordx4 v142, s[74:75]
	s_mov_b32 m0, s30
	ds_read_b128 v[224:227], v166 offset:56320
	global_load_lds_dwordx4 v138, s[28:29]
	s_add_i32 m0, s30, 0x2000
	ds_read_b128 v[220:223], v166 offset:55296
	global_load_lds_dwordx4 v142, s[28:29]
	s_mov_b32 m0, s49
	ds_read_b128 v[216:219], v166 offset:54272
	global_load_lds_dwordx4 v136, s[76:77]
	s_mov_b32 m0, s50
	ds_read_b128 v[212:215], v166 offset:53248
	global_load_lds_dwordx4 v140, s[76:77]
	s_waitcnt vmcnt(8)
	s_waitcnt lgkmcnt(0)
	s_barrier
	s_setprio 1
	v_mfma_f32_16x16x32_bf16 v[68:71], v[172:175], v[152:155], v[68:71]
	v_mfma_f32_16x16x32_bf16 v[64:67], v[180:183], v[152:155], v[64:67]
	v_mfma_f32_16x16x32_bf16 v[52:55], v[172:175], v[204:207], v[52:55]
	v_mfma_f32_16x16x32_bf16 v[48:51], v[180:183], v[204:207], v[48:51]
	v_mfma_f32_16x16x32_bf16 v[36:39], v[172:175], v[212:215], v[36:39]
	v_mfma_f32_16x16x32_bf16 v[32:35], v[180:183], v[212:215], v[32:35]
	v_mfma_f32_16x16x32_bf16 v[20:23], v[172:175], v[220:223], v[20:23]
	v_mfma_f32_16x16x32_bf16 v[16:19], v[180:183], v[220:223], v[16:19]
	v_mfma_f32_16x16x32_bf16 v[68:71], v[176:179], v[168:171], v[68:71]
	v_mfma_f32_16x16x32_bf16 v[64:67], v[184:187], v[168:171], v[64:67]
	v_mfma_f32_16x16x32_bf16 v[52:55], v[176:179], v[208:211], v[52:55]
	v_mfma_f32_16x16x32_bf16 v[48:51], v[184:187], v[208:211], v[48:51]
	v_mfma_f32_16x16x32_bf16 v[36:39], v[176:179], v[216:219], v[36:39]
	v_mfma_f32_16x16x32_bf16 v[32:35], v[184:187], v[216:219], v[32:35]
	v_mfma_f32_16x16x32_bf16 v[20:23], v[176:179], v[224:227], v[20:23]
	v_mfma_f32_16x16x32_bf16 v[16:19], v[184:187], v[224:227], v[16:19]
	s_setprio 0
	s_setprio 1
	v_mfma_f32_16x16x32_bf16 v[60:63], v[188:191], v[152:155], v[60:63]
	v_mfma_f32_16x16x32_bf16 v[56:59], v[196:199], v[152:155], v[56:59]
	v_mfma_f32_16x16x32_bf16 v[44:47], v[188:191], v[204:207], v[44:47]
	v_mfma_f32_16x16x32_bf16 v[40:43], v[196:199], v[204:207], v[40:43]
	v_mfma_f32_16x16x32_bf16 v[28:31], v[188:191], v[212:215], v[28:31]
	v_mfma_f32_16x16x32_bf16 v[24:27], v[196:199], v[212:215], v[24:27]
	v_mfma_f32_16x16x32_bf16 v[10:13], v[188:191], v[220:223], v[12:15]
	v_mfma_f32_16x16x32_bf16 v[6:9], v[196:199], v[220:223], v[6:9]
	v_mfma_f32_16x16x32_bf16 v[60:63], v[192:195], v[168:171], v[60:63]
	v_mfma_f32_16x16x32_bf16 v[56:59], v[200:203], v[168:171], v[56:59]
	v_mfma_f32_16x16x32_bf16 v[44:47], v[192:195], v[208:211], v[44:47]
	v_mfma_f32_16x16x32_bf16 v[40:43], v[200:203], v[208:211], v[40:43]
	v_mfma_f32_16x16x32_bf16 v[28:31], v[192:195], v[216:219], v[28:31]
	v_mfma_f32_16x16x32_bf16 v[24:27], v[200:203], v[216:219], v[24:27]
	v_mfma_f32_16x16x32_bf16 v[12:15], v[192:195], v[224:227], v[10:13]
	v_mfma_f32_16x16x32_bf16 v[8:11], v[200:203], v[224:227], v[6:9]
	s_setprio 0
	s_barrier
	s_add_u32 s26, s26, 0x100
	s_addc_u32 s27, s27, 0
	s_add_u32 s69, s69, 0x100
	s_addc_u32 s70, s70, 0
	s_cmp_ge_i32 s8, s63
	s_cbranch_scc0 .LBB0_1018

.LBB0_1238:
	s_add_i32 s74, s38, 2
	s_add_u32 s39, s36, 0xfff80080
	s_addc_u32 s40, s37, -1
	s_cmp_eq_u32 s71, s38
	s_cselect_b32 s41, s67, s40
	s_cselect_b32 s40, s68, s39
	ds_read_b128 v[140:143], v177
	ds_read_b128 v[144:147], v177 offset:1024
	ds_read_b128 v[148:151], v177 offset:2048
	ds_read_b128 v[152:155], v177 offset:3072
	ds_read_b128 v[156:159], v177 offset:16384
	ds_read_b128 v[160:163], v177 offset:17408
	ds_read_b128 v[164:167], v177 offset:18432
	ds_read_b128 v[168:171], v177 offset:19456
	s_cselect_b32 s38, s70, s72
	s_cselect_b32 s39, s69, s73
	s_add_i32 m0, s45, 0xc000
	ds_read_b128 v[180:183], v178
	ds_read_b128 v[184:187], v178 offset:1024
	ds_read_b128 v[188:191], v178 offset:2048
	ds_read_b128 v[192:195], v178 offset:3072
	ds_read_b128 v[196:199], v178 offset:4096
	ds_read_b128 v[200:203], v178 offset:5120
	ds_read_b128 v[204:207], v178 offset:6144
	global_load_lds_dwordx4 v136, s[36:37]
	s_add_i32 m0, s45, 0xe000
	ds_read_b128 v[208:211], v178 offset:7168
	global_load_lds_dwordx4 v138, s[36:37]
	s_waitcnt vmcnt(8)
	s_waitcnt lgkmcnt(0)
	s_barrier
	s_setprio 1
	v_mfma_i32_16x16x64_i8 v[124:127], v[140:143], v[180:183], v[124:127]
	v_mfma_i32_16x16x64_i8 v[120:123], v[148:151], v[180:183], v[120:123]
	v_mfma_i32_16x16x64_i8 v[116:119], v[140:143], v[188:191], v[116:119]
	v_mfma_i32_16x16x64_i8 v[112:115], v[148:151], v[188:191], v[112:115]
	v_mfma_i32_16x16x64_i8 v[104:107], v[140:143], v[196:199], v[104:107]
	v_mfma_i32_16x16x64_i8 v[96:99], v[148:151], v[196:199], v[96:99]
	v_mfma_i32_16x16x64_i8 v[88:91], v[140:143], v[204:207], v[88:91]
	v_mfma_i32_16x16x64_i8 v[80:83], v[148:151], v[204:207], v[80:83]
	v_mfma_i32_16x16x64_i8 v[124:127], v[144:147], v[184:187], v[124:127]
	v_mfma_i32_16x16x64_i8 v[120:123], v[152:155], v[184:187], v[120:123]
	v_mfma_i32_16x16x64_i8 v[116:119], v[144:147], v[192:195], v[116:119]
	v_mfma_i32_16x16x64_i8 v[112:115], v[152:155], v[192:195], v[112:115]
	v_mfma_i32_16x16x64_i8 v[104:107], v[144:147], v[200:203], v[104:107]
	v_mfma_i32_16x16x64_i8 v[96:99], v[152:155], v[200:203], v[96:99]
	v_mfma_i32_16x16x64_i8 v[88:91], v[144:147], v[208:211], v[88:91]
	v_mfma_i32_16x16x64_i8 v[80:83], v[152:155], v[208:211], v[80:83]
	s_setprio 0
	s_setprio 1
	v_mfma_i32_16x16x64_i8 v[108:111], v[156:159], v[180:183], v[108:111]
	v_mfma_i32_16x16x64_i8 v[100:103], v[164:167], v[180:183], v[100:103]
	v_mfma_i32_16x16x64_i8 v[92:95], v[156:159], v[188:191], v[92:95]
	v_mfma_i32_16x16x64_i8 v[84:87], v[164:167], v[188:191], v[84:87]
	v_mfma_i32_16x16x64_i8 v[76:79], v[156:159], v[196:199], v[76:79]
	v_mfma_i32_16x16x64_i8 v[72:75], v[164:167], v[196:199], v[72:75]
	v_mfma_i32_16x16x64_i8 v[68:71], v[156:159], v[204:207], v[68:71]
	v_mfma_i32_16x16x64_i8 v[64:67], v[164:167], v[204:207], v[64:67]
	v_mfma_i32_16x16x64_i8 v[108:111], v[160:163], v[184:187], v[108:111]
	v_mfma_i32_16x16x64_i8 v[100:103], v[168:171], v[184:187], v[100:103]
	v_mfma_i32_16x16x64_i8 v[92:95], v[160:163], v[192:195], v[92:95]
	v_mfma_i32_16x16x64_i8 v[84:87], v[168:171], v[192:195], v[84:87]
	v_mfma_i32_16x16x64_i8 v[76:79], v[160:163], v[200:203], v[76:79]
	v_mfma_i32_16x16x64_i8 v[72:75], v[168:171], v[200:203], v[72:75]
	v_mfma_i32_16x16x64_i8 v[68:71], v[160:163], v[208:211], v[68:71]
	v_mfma_i32_16x16x64_i8 v[64:67], v[168:171], v[208:211], v[64:67]
	s_setprio 0
	s_barrier
	s_add_i32 s75, s55, s42
	s_mov_b32 m0, s75
	ds_read_b128 v[180:183], v178 offset:16384
	ds_read_b128 v[184:187], v178 offset:17408
	ds_read_b128 v[188:191], v178 offset:18432
	ds_read_b128 v[192:195], v178 offset:19456
	global_load_lds_dwordx4 v130, s[38:39]
	s_add_i32 m0, s75, 0x2000
	s_add_u32 s76, s38, 0x80000
	s_addc_u32 s77, s39, 0
	s_add_i32 s75, s60, s42
	global_load_lds_dwordx4 v134, s[38:39]
	s_mov_b32 m0, s75
	ds_read_b128 v[208:211], v178 offset:23552
	global_load_lds_dwordx4 v130, s[76:77]
	s_add_i32 m0, s75, 0x2000
	ds_read_b128 v[204:207], v178 offset:22528
	global_load_lds_dwordx4 v134, s[76:77]
	s_mov_b32 m0, s45
	ds_read_b128 v[200:203], v178 offset:21504
	global_load_lds_dwordx4 v128, s[40:41]
	s_mov_b32 m0, s46
	ds_read_b128 v[196:199], v178 offset:20480
	global_load_lds_dwordx4 v132, s[40:41]
	s_waitcnt vmcnt(8)
	s_waitcnt lgkmcnt(0)
	s_barrier
	s_setprio 1
	v_mfma_i32_16x16x64_i8 v[60:63], v[140:143], v[180:183], v[60:63]
	v_mfma_i32_16x16x64_i8 v[56:59], v[148:151], v[180:183], v[56:59]
	v_mfma_i32_16x16x64_i8 v[52:55], v[140:143], v[188:191], v[52:55]
	v_mfma_i32_16x16x64_i8 v[48:51], v[148:151], v[188:191], v[48:51]
	v_mfma_i32_16x16x64_i8 v[40:43], v[140:143], v[196:199], v[40:43]
	v_mfma_i32_16x16x64_i8 v[32:35], v[148:151], v[196:199], v[32:35]
	v_mfma_i32_16x16x64_i8 v[24:27], v[140:143], v[204:207], v[24:27]
	v_mfma_i32_16x16x64_i8 v[16:19], v[148:151], v[204:207], v[16:19]
	v_mfma_i32_16x16x64_i8 v[60:63], v[144:147], v[184:187], v[60:63]
	v_mfma_i32_16x16x64_i8 v[56:59], v[152:155], v[184:187], v[56:59]
	v_mfma_i32_16x16x64_i8 v[52:55], v[144:147], v[192:195], v[52:55]
	v_mfma_i32_16x16x64_i8 v[48:51], v[152:155], v[192:195], v[48:51]
	v_mfma_i32_16x16x64_i8 v[40:43], v[144:147], v[200:203], v[40:43]
	v_mfma_i32_16x16x64_i8 v[32:35], v[152:155], v[200:203], v[32:35]
	v_mfma_i32_16x16x64_i8 v[24:27], v[144:147], v[208:211], v[24:27]
	v_mfma_i32_16x16x64_i8 v[16:19], v[152:155], v[208:211], v[16:19]
	s_setprio 0
	s_setprio 1
	v_mfma_i32_16x16x64_i8 v[44:47], v[156:159], v[180:183], v[44:47]
	v_mfma_i32_16x16x64_i8 v[36:39], v[164:167], v[180:183], v[36:39]
	v_mfma_i32_16x16x64_i8 v[28:31], v[156:159], v[188:191], v[28:31]
	v_mfma_i32_16x16x64_i8 v[20:23], v[164:167], v[188:191], v[20:23]
	v_mfma_i32_16x16x64_i8 v[12:15], v[156:159], v[196:199], v[12:15]
	v_mfma_i32_16x16x64_i8 v[8:11], v[164:167], v[196:199], v[8:11]
	v_mfma_i32_16x16x64_i8 v[4:7], v[156:159], v[204:207], v[4:7]
	v_mfma_i32_16x16x64_i8 v[0:3], v[164:167], v[204:207], v[0:3]
	v_mfma_i32_16x16x64_i8 v[44:47], v[160:163], v[184:187], v[44:47]
	v_mfma_i32_16x16x64_i8 v[36:39], v[168:171], v[184:187], v[36:39]
	v_mfma_i32_16x16x64_i8 v[28:31], v[160:163], v[192:195], v[28:31]
	v_mfma_i32_16x16x64_i8 v[20:23], v[168:171], v[192:195], v[20:23]
	v_mfma_i32_16x16x64_i8 v[12:15], v[160:163], v[200:203], v[12:15]
	v_mfma_i32_16x16x64_i8 v[8:11], v[168:171], v[200:203], v[8:11]
	v_mfma_i32_16x16x64_i8 v[4:7], v[160:163], v[208:211], v[4:7]
	v_mfma_i32_16x16x64_i8 v[0:3], v[168:171], v[208:211], v[0:3]
	s_setprio 0
	s_barrier
	s_add_i32 s75, 0, 0x18000
	s_add_i32 s76, 0, 0x1c000
	ds_read_b128 v[140:143], v177 offset:32768
	ds_read_b128 v[144:147], v177 offset:33792
	ds_read_b128 v[148:151], v177 offset:34816
	ds_read_b128 v[152:155], v177 offset:35840
	ds_read_b128 v[156:159], v177 offset:49152
	ds_read_b128 v[160:163], v177 offset:50176
	ds_read_b128 v[164:167], v177 offset:51200
	ds_read_b128 v[168:171], v177 offset:52224
	s_add_u32 s40, s40, 0x80000
	s_addc_u32 s41, s41, 0
	s_mov_b32 m0, s47
	ds_read_b128 v[180:183], v178 offset:32768
	ds_read_b128 v[184:187], v178 offset:33792
	ds_read_b128 v[188:191], v178 offset:34816
	ds_read_b128 v[192:195], v178 offset:35840
	ds_read_b128 v[196:199], v178 offset:36864
	ds_read_b128 v[200:203], v178 offset:37888
	ds_read_b128 v[204:207], v178 offset:38912
	global_load_lds_dwordx4 v128, s[40:41]
	s_mov_b32 m0, s48
	ds_read_b128 v[208:211], v178 offset:39936
	global_load_lds_dwordx4 v132, s[40:41]
	s_waitcnt vmcnt(8)
	s_waitcnt lgkmcnt(0)
	s_barrier
	s_setprio 1
	v_mfma_i32_16x16x64_i8 v[124:127], v[140:143], v[180:183], v[124:127]
	v_mfma_i32_16x16x64_i8 v[120:123], v[148:151], v[180:183], v[120:123]
	v_mfma_i32_16x16x64_i8 v[116:119], v[140:143], v[188:191], v[116:119]
	v_mfma_i32_16x16x64_i8 v[112:115], v[148:151], v[188:191], v[112:115]
	v_mfma_i32_16x16x64_i8 v[104:107], v[140:143], v[196:199], v[104:107]
	v_mfma_i32_16x16x64_i8 v[96:99], v[148:151], v[196:199], v[96:99]
	v_mfma_i32_16x16x64_i8 v[88:91], v[140:143], v[204:207], v[88:91]
	v_mfma_i32_16x16x64_i8 v[80:83], v[148:151], v[204:207], v[80:83]
	v_mfma_i32_16x16x64_i8 v[124:127], v[144:147], v[184:187], v[124:127]
	v_mfma_i32_16x16x64_i8 v[120:123], v[152:155], v[184:187], v[120:123]
	v_mfma_i32_16x16x64_i8 v[116:119], v[144:147], v[192:195], v[116:119]
	v_mfma_i32_16x16x64_i8 v[112:115], v[152:155], v[192:195], v[112:115]
	v_mfma_i32_16x16x64_i8 v[104:107], v[144:147], v[200:203], v[104:107]
	v_mfma_i32_16x16x64_i8 v[96:99], v[152:155], v[200:203], v[96:99]
	v_mfma_i32_16x16x64_i8 v[88:91], v[144:147], v[208:211], v[88:91]
	v_mfma_i32_16x16x64_i8 v[80:83], v[152:155], v[208:211], v[80:83]
	s_setprio 0
	s_setprio 1
	v_mfma_i32_16x16x64_i8 v[108:111], v[156:159], v[180:183], v[108:111]
	v_mfma_i32_16x16x64_i8 v[100:103], v[164:167], v[180:183], v[100:103]
	v_mfma_i32_16x16x64_i8 v[92:95], v[156:159], v[188:191], v[92:95]
	v_mfma_i32_16x16x64_i8 v[84:87], v[164:167], v[188:191], v[84:87]
	v_mfma_i32_16x16x64_i8 v[76:79], v[156:159], v[196:199], v[76:79]
	v_mfma_i32_16x16x64_i8 v[72:75], v[164:167], v[196:199], v[72:75]
	v_mfma_i32_16x16x64_i8 v[68:71], v[156:159], v[204:207], v[68:71]
	v_mfma_i32_16x16x64_i8 v[64:67], v[164:167], v[204:207], v[64:67]
	v_mfma_i32_16x16x64_i8 v[108:111], v[160:163], v[184:187], v[108:111]
	v_mfma_i32_16x16x64_i8 v[100:103], v[168:171], v[184:187], v[100:103]
	v_mfma_i32_16x16x64_i8 v[92:95], v[160:163], v[192:195], v[92:95]
	v_mfma_i32_16x16x64_i8 v[84:87], v[168:171], v[192:195], v[84:87]
	v_mfma_i32_16x16x64_i8 v[76:79], v[160:163], v[200:203], v[76:79]
	v_mfma_i32_16x16x64_i8 v[72:75], v[168:171], v[200:203], v[72:75]
	v_mfma_i32_16x16x64_i8 v[68:71], v[160:163], v[208:211], v[68:71]
	v_mfma_i32_16x16x64_i8 v[64:67], v[168:171], v[208:211], v[64:67]
	s_setprio 0
	s_barrier
	s_add_u32 s98, s38, s20
	s_addc_u32 s99, s39, s21
	s_add_u32 s100, s40, s20
	s_addc_u32 s101, s41, s21
	s_sub_u32 s100, s100, 0x80000
	s_subb_u32 s101, s101, 0
	s_add_i32 s40, s75, s42
	s_mov_b32 m0, s40
	ds_read_b128 v[180:183], v178 offset:49152
	ds_read_b128 v[184:187], v178 offset:50176
	ds_read_b128 v[188:191], v178 offset:51200
	ds_read_b128 v[192:195], v178 offset:52224
	global_load_lds_dwordx4 v130, s[98:99]
	s_add_i32 m0, s40, 0x2000
	s_add_u32 s38, s38, 0x80080
	s_addc_u32 s39, s39, 0
	s_add_i32 s40, s76, s42
	global_load_lds_dwordx4 v134, s[98:99]
	s_mov_b32 m0, s40
	ds_read_b128 v[208:211], v178 offset:56320
	global_load_lds_dwordx4 v130, s[38:39]
	s_add_i32 m0, s40, 0x2000
	ds_read_b128 v[204:207], v178 offset:55296
	global_load_lds_dwordx4 v134, s[38:39]
	s_mov_b32 m0, s51
	ds_read_b128 v[200:203], v178 offset:54272
	global_load_lds_dwordx4 v128, s[100:101]
	s_mov_b32 m0, s52
	ds_read_b128 v[196:199], v178 offset:53248
	global_load_lds_dwordx4 v132, s[100:101]
	s_waitcnt vmcnt(8)
	s_waitcnt lgkmcnt(0)
	s_barrier
	s_setprio 1
	v_mfma_i32_16x16x64_i8 v[60:63], v[140:143], v[180:183], v[60:63]
	v_mfma_i32_16x16x64_i8 v[56:59], v[148:151], v[180:183], v[56:59]
	v_mfma_i32_16x16x64_i8 v[52:55], v[140:143], v[188:191], v[52:55]
	v_mfma_i32_16x16x64_i8 v[48:51], v[148:151], v[188:191], v[48:51]
	v_mfma_i32_16x16x64_i8 v[40:43], v[140:143], v[196:199], v[40:43]
	v_mfma_i32_16x16x64_i8 v[32:35], v[148:151], v[196:199], v[32:35]
	v_mfma_i32_16x16x64_i8 v[24:27], v[140:143], v[204:207], v[24:27]
	v_mfma_i32_16x16x64_i8 v[16:19], v[148:151], v[204:207], v[16:19]
	v_mfma_i32_16x16x64_i8 v[60:63], v[144:147], v[184:187], v[60:63]
	v_mfma_i32_16x16x64_i8 v[56:59], v[152:155], v[184:187], v[56:59]
	v_mfma_i32_16x16x64_i8 v[52:55], v[144:147], v[192:195], v[52:55]
	v_mfma_i32_16x16x64_i8 v[48:51], v[152:155], v[192:195], v[48:51]
	v_mfma_i32_16x16x64_i8 v[40:43], v[144:147], v[200:203], v[40:43]
	v_mfma_i32_16x16x64_i8 v[32:35], v[152:155], v[200:203], v[32:35]
	v_mfma_i32_16x16x64_i8 v[24:27], v[144:147], v[208:211], v[24:27]
	v_mfma_i32_16x16x64_i8 v[16:19], v[152:155], v[208:211], v[16:19]
	s_setprio 0
	s_setprio 1
	v_mfma_i32_16x16x64_i8 v[44:47], v[156:159], v[180:183], v[44:47]
	v_mfma_i32_16x16x64_i8 v[36:39], v[164:167], v[180:183], v[36:39]
	v_mfma_i32_16x16x64_i8 v[28:31], v[156:159], v[188:191], v[28:31]
	v_mfma_i32_16x16x64_i8 v[20:23], v[164:167], v[188:191], v[20:23]
	v_mfma_i32_16x16x64_i8 v[12:15], v[156:159], v[196:199], v[12:15]
	v_mfma_i32_16x16x64_i8 v[8:11], v[164:167], v[196:199], v[8:11]
	v_mfma_i32_16x16x64_i8 v[4:7], v[156:159], v[204:207], v[4:7]
	v_mfma_i32_16x16x64_i8 v[0:3], v[164:167], v[204:207], v[0:3]
	v_mfma_i32_16x16x64_i8 v[44:47], v[160:163], v[184:187], v[44:47]
	v_mfma_i32_16x16x64_i8 v[36:39], v[168:171], v[184:187], v[36:39]
	v_mfma_i32_16x16x64_i8 v[28:31], v[160:163], v[192:195], v[28:31]
	v_mfma_i32_16x16x64_i8 v[20:23], v[168:171], v[192:195], v[20:23]
	v_mfma_i32_16x16x64_i8 v[12:15], v[160:163], v[200:203], v[12:15]
	v_mfma_i32_16x16x64_i8 v[8:11], v[168:171], v[200:203], v[8:11]
	v_mfma_i32_16x16x64_i8 v[4:7], v[160:163], v[208:211], v[4:7]
	v_mfma_i32_16x16x64_i8 v[0:3], v[168:171], v[208:211], v[0:3]
	s_setprio 0
	s_barrier
	s_add_u32 s36, s36, 0x100
	s_addc_u32 s37, s37, 0
	s_add_u32 s72, s72, 0x100
	s_addc_u32 s73, s73, 0
	s_cmp_ge_i32 s74, s8
	s_mov_b32 s38, s74
	s_cbranch_scc0 .LBB0_1238

.Lq_body_L:
	s_add_i32 s74, s38, 2
	s_add_u32 s39, s36, 0xfff80080
	s_addc_u32 s40, s37, -1
	s_cmp_eq_u32 s71, s38
	s_cselect_b32 s41, s67, s40
	s_cselect_b32 s40, s68, s39
	ds_read_b128 v[140:143], v177
	ds_read_b128 v[144:147], v177 offset:1024
	ds_read_b128 v[148:151], v177 offset:2048
	ds_read_b128 v[152:155], v177 offset:3072
	ds_read_b128 v[156:159], v177 offset:16384
	ds_read_b128 v[160:163], v177 offset:17408
	ds_read_b128 v[164:167], v177 offset:18432
	ds_read_b128 v[168:171], v177 offset:19456
	s_cselect_b32 s38, s70, s72
	s_cselect_b32 s39, s69, s73
	s_add_i32 m0, s45, 0xc000
	ds_read_b128 v[180:183], v178
	ds_read_b128 v[184:187], v178 offset:1024
	ds_read_b128 v[188:191], v178 offset:2048
	ds_read_b128 v[192:195], v178 offset:3072
	ds_read_b128 v[196:199], v178 offset:4096
	ds_read_b128 v[200:203], v178 offset:5120
	ds_read_b128 v[204:207], v178 offset:6144
	global_load_lds_dwordx4 v136, s[36:37]
	s_add_i32 m0, s45, 0xe000
	ds_read_b128 v[208:211], v178 offset:7168
	global_load_lds_dwordx4 v138, s[36:37]
	global_load_dwordx4 v[226:229], v223, s[100:101] nt
	s_add_u32 s84, s84, 1
	s_waitcnt vmcnt(9)
	s_waitcnt lgkmcnt(0)
	s_barrier
	s_setprio 1
	v_mfma_i32_16x16x64_i8 v[124:127], v[140:143], v[180:183], v[124:127]
	v_mfma_i32_16x16x64_i8 v[120:123], v[148:151], v[180:183], v[120:123]
	v_mfma_i32_16x16x64_i8 v[116:119], v[140:143], v[188:191], v[116:119]
	v_mfma_i32_16x16x64_i8 v[112:115], v[148:151], v[188:191], v[112:115]
	v_mfma_i32_16x16x64_i8 v[104:107], v[140:143], v[196:199], v[104:107]
	v_mfma_i32_16x16x64_i8 v[96:99], v[148:151], v[196:199], v[96:99]
	v_mfma_i32_16x16x64_i8 v[88:91], v[140:143], v[204:207], v[88:91]
	v_mfma_i32_16x16x64_i8 v[80:83], v[148:151], v[204:207], v[80:83]
	v_mfma_i32_16x16x64_i8 v[124:127], v[144:147], v[184:187], v[124:127]
	v_mfma_i32_16x16x64_i8 v[120:123], v[152:155], v[184:187], v[120:123]
	v_mfma_i32_16x16x64_i8 v[116:119], v[144:147], v[192:195], v[116:119]
	v_mfma_i32_16x16x64_i8 v[112:115], v[152:155], v[192:195], v[112:115]
	v_mfma_i32_16x16x64_i8 v[104:107], v[144:147], v[200:203], v[104:107]
	v_mfma_i32_16x16x64_i8 v[96:99], v[152:155], v[200:203], v[96:99]
	v_mfma_i32_16x16x64_i8 v[88:91], v[144:147], v[208:211], v[88:91]
	v_mfma_i32_16x16x64_i8 v[80:83], v[152:155], v[208:211], v[80:83]
	s_setprio 0
	s_setprio 1
	v_mfma_i32_16x16x64_i8 v[108:111], v[156:159], v[180:183], v[108:111]
	v_mfma_i32_16x16x64_i8 v[100:103], v[164:167], v[180:183], v[100:103]
	v_mfma_i32_16x16x64_i8 v[92:95], v[156:159], v[188:191], v[92:95]
	v_mfma_i32_16x16x64_i8 v[84:87], v[164:167], v[188:191], v[84:87]
	v_mfma_i32_16x16x64_i8 v[76:79], v[156:159], v[196:199], v[76:79]
	v_mfma_i32_16x16x64_i8 v[72:75], v[164:167], v[196:199], v[72:75]
	v_mfma_i32_16x16x64_i8 v[68:71], v[156:159], v[204:207], v[68:71]
	v_mfma_i32_16x16x64_i8 v[64:67], v[164:167], v[204:207], v[64:67]
	v_mfma_i32_16x16x64_i8 v[108:111], v[160:163], v[184:187], v[108:111]
	v_mfma_i32_16x16x64_i8 v[100:103], v[168:171], v[184:187], v[100:103]
	v_mfma_i32_16x16x64_i8 v[92:95], v[160:163], v[192:195], v[92:95]
	v_mfma_i32_16x16x64_i8 v[84:87], v[168:171], v[192:195], v[84:87]
	v_mfma_i32_16x16x64_i8 v[76:79], v[160:163], v[200:203], v[76:79]
	v_mfma_i32_16x16x64_i8 v[72:75], v[168:171], v[200:203], v[72:75]
	v_mfma_i32_16x16x64_i8 v[68:71], v[160:163], v[208:211], v[68:71]
	v_mfma_i32_16x16x64_i8 v[64:67], v[168:171], v[208:211], v[64:67]
	s_setprio 0
	s_barrier
	s_add_i32 s75, s55, s42
	v_lshl_add_u64 v[172:173], s[38:39], 0, v[130:131]
	s_mov_b32 m0, s75
	ds_read_b128 v[180:183], v178 offset:16384
	ds_read_b128 v[184:187], v178 offset:17408
	ds_read_b128 v[188:191], v178 offset:18432
	ds_read_b128 v[192:195], v178 offset:19456
	ds_read_b128 v[196:199], v178 offset:20480
	global_load_lds_dwordx4 v130, s[38:39]
	s_add_i32 m0, s75, 0x2000
	s_add_u32 s76, s38, 0x80000
	v_lshl_add_u64 v[212:213], s[38:39], 0, v[134:135]
	s_addc_u32 s77, s39, 0
	s_add_i32 s75, s60, s42
	global_load_lds_dwordx4 v134, s[38:39]
	s_mov_b32 m0, s75
	v_lshl_add_u64 v[216:217], s[40:41], 0, v[132:133]
	global_load_lds_dwordx4 v130, s[76:77]
	s_add_i32 m0, s75, 0x2000
	ds_read_b128 v[208:211], v178 offset:23552
	global_load_lds_dwordx4 v134, s[76:77]
	v_lshl_add_u64 v[214:215], s[40:41], 0, v[128:129]
	s_mov_b32 m0, s45
	ds_read_b128 v[204:207], v178 offset:22528
	global_load_lds_dwordx4 v128, s[40:41]
	s_mov_b32 m0, s46
	ds_read_b128 v[200:203], v178 offset:21504
	global_load_lds_dwordx4 v132, s[40:41]
	s_waitcnt vmcnt(9)
	s_waitcnt lgkmcnt(0)
	s_barrier
	s_setprio 1
	v_mfma_i32_16x16x64_i8 v[60:63], v[140:143], v[180:183], v[60:63]
	v_mfma_i32_16x16x64_i8 v[56:59], v[148:151], v[180:183], v[56:59]
	v_mfma_i32_16x16x64_i8 v[52:55], v[140:143], v[188:191], v[52:55]
	v_mfma_i32_16x16x64_i8 v[48:51], v[148:151], v[188:191], v[48:51]
	v_mfma_i32_16x16x64_i8 v[40:43], v[140:143], v[196:199], v[40:43]
	v_mfma_i32_16x16x64_i8 v[32:35], v[148:151], v[196:199], v[32:35]
	v_mfma_i32_16x16x64_i8 v[24:27], v[140:143], v[204:207], v[24:27]
	v_mfma_i32_16x16x64_i8 v[16:19], v[148:151], v[204:207], v[16:19]
	v_mfma_i32_16x16x64_i8 v[60:63], v[144:147], v[184:187], v[60:63]
	v_mfma_i32_16x16x64_i8 v[56:59], v[152:155], v[184:187], v[56:59]
	v_mfma_i32_16x16x64_i8 v[52:55], v[144:147], v[192:195], v[52:55]
	v_mfma_i32_16x16x64_i8 v[48:51], v[152:155], v[192:195], v[48:51]
	v_mfma_i32_16x16x64_i8 v[40:43], v[144:147], v[200:203], v[40:43]
	v_mfma_i32_16x16x64_i8 v[32:35], v[152:155], v[200:203], v[32:35]
	v_mfma_i32_16x16x64_i8 v[24:27], v[144:147], v[208:211], v[24:27]
	v_mfma_i32_16x16x64_i8 v[16:19], v[152:155], v[208:211], v[16:19]
	s_setprio 0
	s_setprio 1
	v_mfma_i32_16x16x64_i8 v[44:47], v[156:159], v[180:183], v[44:47]
	v_mfma_i32_16x16x64_i8 v[36:39], v[164:167], v[180:183], v[36:39]
	v_mfma_i32_16x16x64_i8 v[28:31], v[156:159], v[188:191], v[28:31]
	v_mfma_i32_16x16x64_i8 v[20:23], v[164:167], v[188:191], v[20:23]
	v_mfma_i32_16x16x64_i8 v[12:15], v[156:159], v[196:199], v[12:15]
	v_mfma_i32_16x16x64_i8 v[8:11], v[164:167], v[196:199], v[8:11]
	v_mfma_i32_16x16x64_i8 v[4:7], v[156:159], v[204:207], v[4:7]
	v_mfma_i32_16x16x64_i8 v[0:3], v[164:167], v[204:207], v[0:3]
	v_mfma_i32_16x16x64_i8 v[44:47], v[160:163], v[184:187], v[44:47]
	v_mfma_i32_16x16x64_i8 v[36:39], v[168:171], v[184:187], v[36:39]
	v_mfma_i32_16x16x64_i8 v[28:31], v[160:163], v[192:195], v[28:31]
	v_mfma_i32_16x16x64_i8 v[20:23], v[168:171], v[192:195], v[20:23]
	v_mfma_i32_16x16x64_i8 v[12:15], v[160:163], v[200:203], v[12:15]
	v_mfma_i32_16x16x64_i8 v[8:11], v[168:171], v[200:203], v[8:11]
	v_mfma_i32_16x16x64_i8 v[4:7], v[160:163], v[208:211], v[4:7]
	v_mfma_i32_16x16x64_i8 v[0:3], v[168:171], v[208:211], v[0:3]
	s_setprio 0
	s_barrier
	s_add_i32 s75, 0, 0x18000
	s_add_i32 s76, 0, 0x1c000
	ds_read_b128 v[140:143], v177 offset:32768
	ds_read_b128 v[144:147], v177 offset:33792
	ds_read_b128 v[148:151], v177 offset:34816
	ds_read_b128 v[152:155], v177 offset:35840
	ds_read_b128 v[156:159], v177 offset:49152
	ds_read_b128 v[160:163], v177 offset:50176
	ds_read_b128 v[164:167], v177 offset:51200
	ds_read_b128 v[168:171], v177 offset:52224
	s_add_u32 s40, s40, 0x80000
	s_addc_u32 s41, s41, 0
	s_mov_b32 m0, s47
	ds_read_b128 v[180:183], v178 offset:32768
	ds_read_b128 v[184:187], v178 offset:33792
	ds_read_b128 v[188:191], v178 offset:34816
	ds_read_b128 v[192:195], v178 offset:35840
	ds_read_b128 v[196:199], v178 offset:36864
	ds_read_b128 v[200:203], v178 offset:37888
	ds_read_b128 v[204:207], v178 offset:38912
	global_load_lds_dwordx4 v128, s[40:41]
	s_mov_b32 m0, s48
	ds_read_b128 v[208:211], v178 offset:39936
	global_load_lds_dwordx4 v132, s[40:41]
	s_waitcnt vmcnt(9)
	s_waitcnt lgkmcnt(0)
	s_barrier
	s_setprio 1
	v_mfma_i32_16x16x64_i8 v[124:127], v[140:143], v[180:183], v[124:127]
	v_mfma_i32_16x16x64_i8 v[120:123], v[148:151], v[180:183], v[120:123]
	v_mfma_i32_16x16x64_i8 v[116:119], v[140:143], v[188:191], v[116:119]
	v_mfma_i32_16x16x64_i8 v[112:115], v[148:151], v[188:191], v[112:115]
	v_mfma_i32_16x16x64_i8 v[104:107], v[140:143], v[196:199], v[104:107]
	v_mfma_i32_16x16x64_i8 v[96:99], v[148:151], v[196:199], v[96:99]
	v_mfma_i32_16x16x64_i8 v[88:91], v[140:143], v[204:207], v[88:91]
	v_mfma_i32_16x16x64_i8 v[80:83], v[148:151], v[204:207], v[80:83]
	v_mfma_i32_16x16x64_i8 v[124:127], v[144:147], v[184:187], v[124:127]
	v_mfma_i32_16x16x64_i8 v[120:123], v[152:155], v[184:187], v[120:123]
	v_mfma_i32_16x16x64_i8 v[116:119], v[144:147], v[192:195], v[116:119]
	v_mfma_i32_16x16x64_i8 v[112:115], v[152:155], v[192:195], v[112:115]
	v_mfma_i32_16x16x64_i8 v[104:107], v[144:147], v[200:203], v[104:107]
	v_mfma_i32_16x16x64_i8 v[96:99], v[152:155], v[200:203], v[96:99]
	v_mfma_i32_16x16x64_i8 v[88:91], v[144:147], v[208:211], v[88:91]
	v_mfma_i32_16x16x64_i8 v[80:83], v[152:155], v[208:211], v[80:83]
	s_setprio 0
	s_setprio 1
	v_mfma_i32_16x16x64_i8 v[108:111], v[156:159], v[180:183], v[108:111]
	v_mfma_i32_16x16x64_i8 v[100:103], v[164:167], v[180:183], v[100:103]
	v_mfma_i32_16x16x64_i8 v[92:95], v[156:159], v[188:191], v[92:95]
	v_mfma_i32_16x16x64_i8 v[84:87], v[164:167], v[188:191], v[84:87]
	v_mfma_i32_16x16x64_i8 v[76:79], v[156:159], v[196:199], v[76:79]
	v_mfma_i32_16x16x64_i8 v[72:75], v[164:167], v[196:199], v[72:75]
	v_mfma_i32_16x16x64_i8 v[68:71], v[156:159], v[204:207], v[68:71]
	v_mfma_i32_16x16x64_i8 v[64:67], v[164:167], v[204:207], v[64:67]
	v_mfma_i32_16x16x64_i8 v[108:111], v[160:163], v[184:187], v[108:111]
	v_mfma_i32_16x16x64_i8 v[100:103], v[168:171], v[184:187], v[100:103]
	v_mfma_i32_16x16x64_i8 v[92:95], v[160:163], v[192:195], v[92:95]
	v_mfma_i32_16x16x64_i8 v[84:87], v[168:171], v[192:195], v[84:87]
	v_mfma_i32_16x16x64_i8 v[76:79], v[160:163], v[200:203], v[76:79]
	v_mfma_i32_16x16x64_i8 v[72:75], v[168:171], v[200:203], v[72:75]
	v_mfma_i32_16x16x64_i8 v[68:71], v[160:163], v[208:211], v[68:71]
	v_mfma_i32_16x16x64_i8 v[64:67], v[168:171], v[208:211], v[64:67]
	s_setprio 0
	s_barrier
	s_add_i32 s40, s75, s42
	v_lshl_add_u64 v[172:173], v[172:173], 0, s[20:21]
	s_mov_b32 m0, s40
	ds_read_b128 v[180:183], v178 offset:49152
	ds_read_b128 v[184:187], v178 offset:50176
	ds_read_b128 v[188:191], v178 offset:51200
	ds_read_b128 v[192:195], v178 offset:52224
	global_load_lds_dwordx4 v[172:173], off
	s_add_i32 m0, s40, 0x2000
	s_add_u32 s38, s38, 0x80080
	v_lshl_add_u64 v[172:173], v[212:213], 0, s[20:21]
	s_addc_u32 s39, s39, 0
	s_add_i32 s40, s76, s42
	global_load_lds_dwordx4 v[172:173], off
	s_mov_b32 m0, s40
	ds_read_b128 v[208:211], v178 offset:56320
	global_load_lds_dwordx4 v130, s[38:39]
	s_add_i32 m0, s40, 0x2000
	ds_read_b128 v[204:207], v178 offset:55296
	global_load_lds_dwordx4 v134, s[38:39]
	v_lshl_add_u64 v[172:173], v[214:215], 0, s[20:21]
	s_mov_b32 m0, s51
	ds_read_b128 v[200:203], v178 offset:54272
	global_load_lds_dwordx4 v[172:173], off
	v_lshl_add_u64 v[172:173], v[216:217], 0, s[20:21]
	s_mov_b32 m0, s52
	ds_read_b128 v[196:199], v178 offset:53248
	global_load_lds_dwordx4 v[172:173], off
	s_waitcnt vmcnt(8)
	s_waitcnt lgkmcnt(0)
	s_barrier
	s_setprio 1
	v_mfma_i32_16x16x64_i8 v[60:63], v[140:143], v[180:183], v[60:63]
	v_mfma_i32_16x16x64_i8 v[56:59], v[148:151], v[180:183], v[56:59]
	v_mfma_i32_16x16x64_i8 v[52:55], v[140:143], v[188:191], v[52:55]
	v_fmaak_f32 v226, v226, v220, 0x4b400000
	v_mfma_i32_16x16x64_i8 v[48:51], v[148:151], v[188:191], v[48:51]
	v_mfma_i32_16x16x64_i8 v[40:43], v[140:143], v[196:199], v[40:43]
	v_mfma_i32_16x16x64_i8 v[32:35], v[148:151], v[196:199], v[32:35]
	v_fmaak_f32 v227, v227, v225, 0x4b400000
	v_mfma_i32_16x16x64_i8 v[24:27], v[140:143], v[204:207], v[24:27]
	v_mfma_i32_16x16x64_i8 v[16:19], v[148:151], v[204:207], v[16:19]
	v_mfma_i32_16x16x64_i8 v[60:63], v[144:147], v[184:187], v[60:63]
	v_fmaak_f32 v228, v228, v252, 0x4b400000
	v_mfma_i32_16x16x64_i8 v[56:59], v[152:155], v[184:187], v[56:59]
	v_mfma_i32_16x16x64_i8 v[52:55], v[144:147], v[192:195], v[52:55]
	v_mfma_i32_16x16x64_i8 v[48:51], v[152:155], v[192:195], v[48:51]
	v_fmaak_f32 v229, v229, v253, 0x4b400000
	v_mfma_i32_16x16x64_i8 v[40:43], v[144:147], v[200:203], v[40:43]
	v_mfma_i32_16x16x64_i8 v[32:35], v[152:155], v[200:203], v[32:35]
	v_mfma_i32_16x16x64_i8 v[24:27], v[144:147], v[208:211], v[24:27]
	v_alignbit_b32 v239, v226, v239, 8
	v_mfma_i32_16x16x64_i8 v[16:19], v[152:155], v[208:211], v[16:19]
	s_setprio 0
	s_setprio 1
	v_mfma_i32_16x16x64_i8 v[44:47], v[156:159], v[180:183], v[44:47]
	v_mfma_i32_16x16x64_i8 v[36:39], v[164:167], v[180:183], v[36:39]
	v_alignbit_b32 v243, v227, v243, 8
	v_mfma_i32_16x16x64_i8 v[28:31], v[156:159], v[188:191], v[28:31]
	v_mfma_i32_16x16x64_i8 v[20:23], v[164:167], v[188:191], v[20:23]
	v_mfma_i32_16x16x64_i8 v[12:15], v[156:159], v[196:199], v[12:15]
	v_alignbit_b32 v247, v228, v247, 8
	v_mfma_i32_16x16x64_i8 v[8:11], v[164:167], v[196:199], v[8:11]
	v_mfma_i32_16x16x64_i8 v[4:7], v[156:159], v[204:207], v[4:7]
	v_mfma_i32_16x16x64_i8 v[0:3], v[164:167], v[204:207], v[0:3]
	v_alignbit_b32 v251, v229, v251, 8
	v_mfma_i32_16x16x64_i8 v[44:47], v[160:163], v[184:187], v[44:47]
	v_mfma_i32_16x16x64_i8 v[36:39], v[168:171], v[184:187], v[36:39]
	v_mfma_i32_16x16x64_i8 v[28:31], v[160:163], v[192:195], v[28:31]
	v_add_u32_e32 v223, 0x4000, v223
	v_mfma_i32_16x16x64_i8 v[20:23], v[168:171], v[192:195], v[20:23]
	v_mfma_i32_16x16x64_i8 v[12:15], v[160:163], v[200:203], v[12:15]
	v_mfma_i32_16x16x64_i8 v[8:11], v[168:171], v[200:203], v[8:11]
	v_mfma_i32_16x16x64_i8 v[4:7], v[160:163], v[208:211], v[4:7]
	v_mfma_i32_16x16x64_i8 v[0:3], v[168:171], v[208:211], v[0:3]
	s_setprio 0
	s_barrier
	s_and_b32 s77, s84, 3
	s_cbranch_scc0 .Lq_mv_L

.Lq_st_j:
	s_waitcnt vmcnt(13)
	s_waitcnt lgkmcnt(0)
	s_barrier
	s_setprio 1
	v_mfma_i32_16x16x64_i8 v[124:127], v[140:143], v[180:183], v[124:127]
	v_mfma_i32_16x16x64_i8 v[120:123], v[148:151], v[180:183], v[120:123]
	v_mfma_i32_16x16x64_i8 v[116:119], v[140:143], v[188:191], v[116:119]
	v_mfma_i32_16x16x64_i8 v[112:115], v[148:151], v[188:191], v[112:115]
	v_mfma_i32_16x16x64_i8 v[104:107], v[140:143], v[196:199], v[104:107]
	v_mfma_i32_16x16x64_i8 v[96:99], v[148:151], v[196:199], v[96:99]
	v_mfma_i32_16x16x64_i8 v[88:91], v[140:143], v[204:207], v[88:91]
	v_mfma_i32_16x16x64_i8 v[80:83], v[148:151], v[204:207], v[80:83]
	v_mfma_i32_16x16x64_i8 v[124:127], v[144:147], v[184:187], v[124:127]
	v_mfma_i32_16x16x64_i8 v[120:123], v[152:155], v[184:187], v[120:123]
	v_mfma_i32_16x16x64_i8 v[116:119], v[144:147], v[192:195], v[116:119]
	v_mfma_i32_16x16x64_i8 v[112:115], v[152:155], v[192:195], v[112:115]
	v_mfma_i32_16x16x64_i8 v[104:107], v[144:147], v[200:203], v[104:107]
	v_mfma_i32_16x16x64_i8 v[96:99], v[152:155], v[200:203], v[96:99]
	v_mfma_i32_16x16x64_i8 v[88:91], v[144:147], v[208:211], v[88:91]
	v_mfma_i32_16x16x64_i8 v[80:83], v[152:155], v[208:211], v[80:83]
	s_setprio 0
	s_setprio 1
	v_mfma_i32_16x16x64_i8 v[108:111], v[156:159], v[180:183], v[108:111]
	v_mfma_i32_16x16x64_i8 v[100:103], v[164:167], v[180:183], v[100:103]
	v_mfma_i32_16x16x64_i8 v[92:95], v[156:159], v[188:191], v[92:95]
	v_mfma_i32_16x16x64_i8 v[84:87], v[164:167], v[188:191], v[84:87]
	v_mfma_i32_16x16x64_i8 v[76:79], v[156:159], v[196:199], v[76:79]
	v_mfma_i32_16x16x64_i8 v[72:75], v[164:167], v[196:199], v[72:75]
	v_mfma_i32_16x16x64_i8 v[68:71], v[156:159], v[204:207], v[68:71]
	v_mfma_i32_16x16x64_i8 v[64:67], v[164:167], v[204:207], v[64:67]
	v_mfma_i32_16x16x64_i8 v[108:111], v[160:163], v[184:187], v[108:111]
	v_mfma_i32_16x16x64_i8 v[100:103], v[168:171], v[184:187], v[100:103]
	v_mfma_i32_16x16x64_i8 v[92:95], v[160:163], v[192:195], v[92:95]
	v_mfma_i32_16x16x64_i8 v[84:87], v[168:171], v[192:195], v[84:87]
	v_mfma_i32_16x16x64_i8 v[76:79], v[160:163], v[200:203], v[76:79]
	v_mfma_i32_16x16x64_i8 v[72:75], v[168:171], v[200:203], v[72:75]
	v_mfma_i32_16x16x64_i8 v[68:71], v[160:163], v[208:211], v[68:71]
	v_mfma_i32_16x16x64_i8 v[64:67], v[168:171], v[208:211], v[64:67]
	s_setprio 0
	s_barrier
	s_add_i32 s75, s55, s42
	v_lshl_add_u64 v[172:173], s[38:39], 0, v[130:131]
	s_mov_b32 m0, s75
	ds_read_b128 v[180:183], v178 offset:16384
	ds_read_b128 v[184:187], v178 offset:17408
	ds_read_b128 v[188:191], v178 offset:18432
	ds_read_b128 v[192:195], v178 offset:19456
	ds_read_b128 v[196:199], v178 offset:20480
	global_load_lds_dwordx4 v130, s[38:39]
	s_add_i32 m0, s75, 0x2000
	s_add_u32 s76, s38, 0x80000
	v_lshl_add_u64 v[212:213], s[38:39], 0, v[134:135]
	s_addc_u32 s77, s39, 0
	s_add_i32 s75, s60, s42
	global_load_lds_dwordx4 v134, s[38:39]
	s_mov_b32 m0, s75
	v_lshl_add_u64 v[216:217], s[40:41], 0, v[132:133]
	global_load_lds_dwordx4 v130, s[76:77]
	s_add_i32 m0, s75, 0x2000
	ds_read_b128 v[208:211], v178 offset:23552
	global_load_lds_dwordx4 v134, s[76:77]
	v_lshl_add_u64 v[214:215], s[40:41], 0, v[128:129]
	s_mov_b32 m0, s45
	ds_read_b128 v[204:207], v178 offset:22528
	global_load_lds_dwordx4 v128, s[40:41]
	s_mov_b32 m0, s46
	ds_read_b128 v[200:203], v178 offset:21504
	global_load_lds_dwordx4 v132, s[40:41]
	s_waitcnt vmcnt(13)
	s_waitcnt lgkmcnt(0)
	s_barrier
	s_setprio 1
	v_mfma_i32_16x16x64_i8 v[60:63], v[140:143], v[180:183], v[60:63]
	v_mfma_i32_16x16x64_i8 v[56:59], v[148:151], v[180:183], v[56:59]
	v_mfma_i32_16x16x64_i8 v[52:55], v[140:143], v[188:191], v[52:55]
	v_mfma_i32_16x16x64_i8 v[48:51], v[148:151], v[188:191], v[48:51]
	v_mfma_i32_16x16x64_i8 v[40:43], v[140:143], v[196:199], v[40:43]
	v_mfma_i32_16x16x64_i8 v[32:35], v[148:151], v[196:199], v[32:35]
	v_mfma_i32_16x16x64_i8 v[24:27], v[140:143], v[204:207], v[24:27]
	v_mfma_i32_16x16x64_i8 v[16:19], v[148:151], v[204:207], v[16:19]
	v_mfma_i32_16x16x64_i8 v[60:63], v[144:147], v[184:187], v[60:63]
	v_mfma_i32_16x16x64_i8 v[56:59], v[152:155], v[184:187], v[56:59]
	v_mfma_i32_16x16x64_i8 v[52:55], v[144:147], v[192:195], v[52:55]
	v_mfma_i32_16x16x64_i8 v[48:51], v[152:155], v[192:195], v[48:51]
	v_mfma_i32_16x16x64_i8 v[40:43], v[144:147], v[200:203], v[40:43]
	v_mfma_i32_16x16x64_i8 v[32:35], v[152:155], v[200:203], v[32:35]
	v_mfma_i32_16x16x64_i8 v[24:27], v[144:147], v[208:211], v[24:27]
	v_mfma_i32_16x16x64_i8 v[16:19], v[152:155], v[208:211], v[16:19]
	s_setprio 0
	s_setprio 1
	v_mfma_i32_16x16x64_i8 v[44:47], v[156:159], v[180:183], v[44:47]
	v_mfma_i32_16x16x64_i8 v[36:39], v[164:167], v[180:183], v[36:39]
	v_mfma_i32_16x16x64_i8 v[28:31], v[156:159], v[188:191], v[28:31]
	v_mfma_i32_16x16x64_i8 v[20:23], v[164:167], v[188:191], v[20:23]
	v_mfma_i32_16x16x64_i8 v[12:15], v[156:159], v[196:199], v[12:15]
	v_mfma_i32_16x16x64_i8 v[8:11], v[164:167], v[196:199], v[8:11]
	v_mfma_i32_16x16x64_i8 v[4:7], v[156:159], v[204:207], v[4:7]
	v_mfma_i32_16x16x64_i8 v[0:3], v[164:167], v[204:207], v[0:3]
	v_mfma_i32_16x16x64_i8 v[44:47], v[160:163], v[184:187], v[44:47]
	v_mfma_i32_16x16x64_i8 v[36:39], v[168:171], v[184:187], v[36:39]
	v_mfma_i32_16x16x64_i8 v[28:31], v[160:163], v[192:195], v[28:31]
	v_mfma_i32_16x16x64_i8 v[20:23], v[168:171], v[192:195], v[20:23]
	v_mfma_i32_16x16x64_i8 v[12:15], v[160:163], v[200:203], v[12:15]
	v_mfma_i32_16x16x64_i8 v[8:11], v[168:171], v[200:203], v[8:11]
	v_mfma_i32_16x16x64_i8 v[4:7], v[160:163], v[208:211], v[4:7]
	v_mfma_i32_16x16x64_i8 v[0:3], v[168:171], v[208:211], v[0:3]
	s_setprio 0
	s_barrier
	s_add_i32 s75, 0, 0x18000
	s_add_i32 s76, 0, 0x1c000
	ds_read_b128 v[140:143], v177 offset:32768
	ds_read_b128 v[144:147], v177 offset:33792
	ds_read_b128 v[148:151], v177 offset:34816
	ds_read_b128 v[152:155], v177 offset:35840
	ds_read_b128 v[156:159], v177 offset:49152
	ds_read_b128 v[160:163], v177 offset:50176
	ds_read_b128 v[164:167], v177 offset:51200
	ds_read_b128 v[168:171], v177 offset:52224
	s_add_u32 s40, s40, 0x80000
	s_addc_u32 s41, s41, 0
	s_mov_b32 m0, s47
	ds_read_b128 v[180:183], v178 offset:32768
	ds_read_b128 v[184:187], v178 offset:33792
	ds_read_b128 v[188:191], v178 offset:34816
	ds_read_b128 v[192:195], v178 offset:35840
	ds_read_b128 v[196:199], v178 offset:36864
	ds_read_b128 v[200:203], v178 offset:37888
	ds_read_b128 v[204:207], v178 offset:38912
	global_load_lds_dwordx4 v128, s[40:41]
	s_mov_b32 m0, s48
	ds_read_b128 v[208:211], v178 offset:39936
	global_load_lds_dwordx4 v132, s[40:41]
	s_waitcnt vmcnt(13)
	s_waitcnt lgkmcnt(0)
	s_barrier
	s_setprio 1
	v_mfma_i32_16x16x64_i8 v[124:127], v[140:143], v[180:183], v[124:127]
	v_mfma_i32_16x16x64_i8 v[120:123], v[148:151], v[180:183], v[120:123]
	v_mfma_i32_16x16x64_i8 v[116:119], v[140:143], v[188:191], v[116:119]
	v_mfma_i32_16x16x64_i8 v[112:115], v[148:151], v[188:191], v[112:115]
	v_mfma_i32_16x16x64_i8 v[104:107], v[140:143], v[196:199], v[104:107]
	v_mfma_i32_16x16x64_i8 v[96:99], v[148:151], v[196:199], v[96:99]
	v_mfma_i32_16x16x64_i8 v[88:91], v[140:143], v[204:207], v[88:91]
	v_mfma_i32_16x16x64_i8 v[80:83], v[148:151], v[204:207], v[80:83]
	v_mfma_i32_16x16x64_i8 v[124:127], v[144:147], v[184:187], v[124:127]
	v_mfma_i32_16x16x64_i8 v[120:123], v[152:155], v[184:187], v[120:123]
	v_mfma_i32_16x16x64_i8 v[116:119], v[144:147], v[192:195], v[116:119]
	v_mfma_i32_16x16x64_i8 v[112:115], v[152:155], v[192:195], v[112:115]
	v_mfma_i32_16x16x64_i8 v[104:107], v[144:147], v[200:203], v[104:107]
	v_mfma_i32_16x16x64_i8 v[96:99], v[152:155], v[200:203], v[96:99]
	v_mfma_i32_16x16x64_i8 v[88:91], v[144:147], v[208:211], v[88:91]
	v_mfma_i32_16x16x64_i8 v[80:83], v[152:155], v[208:211], v[80:83]
	s_setprio 0
	s_setprio 1
	v_mfma_i32_16x16x64_i8 v[108:111], v[156:159], v[180:183], v[108:111]
	v_mfma_i32_16x16x64_i8 v[100:103], v[164:167], v[180:183], v[100:103]
	v_mfma_i32_16x16x64_i8 v[92:95], v[156:159], v[188:191], v[92:95]
	v_mfma_i32_16x16x64_i8 v[84:87], v[164:167], v[188:191], v[84:87]
	v_mfma_i32_16x16x64_i8 v[76:79], v[156:159], v[196:199], v[76:79]
	v_mfma_i32_16x16x64_i8 v[72:75], v[164:167], v[196:199], v[72:75]
	v_mfma_i32_16x16x64_i8 v[68:71], v[156:159], v[204:207], v[68:71]
	v_mfma_i32_16x16x64_i8 v[64:67], v[164:167], v[204:207], v[64:67]
	v_mfma_i32_16x16x64_i8 v[108:111], v[160:163], v[184:187], v[108:111]
	v_mfma_i32_16x16x64_i8 v[100:103], v[168:171], v[184:187], v[100:103]
	v_mfma_i32_16x16x64_i8 v[92:95], v[160:163], v[192:195], v[92:95]
	v_mfma_i32_16x16x64_i8 v[84:87], v[168:171], v[192:195], v[84:87]
	v_mfma_i32_16x16x64_i8 v[76:79], v[160:163], v[200:203], v[76:79]
	v_mfma_i32_16x16x64_i8 v[72:75], v[168:171], v[200:203], v[72:75]
	v_mfma_i32_16x16x64_i8 v[68:71], v[160:163], v[208:211], v[68:71]
	v_mfma_i32_16x16x64_i8 v[64:67], v[168:171], v[208:211], v[64:67]
	s_setprio 0
	s_barrier
	s_add_i32 s40, s75, s42
	v_lshl_add_u64 v[172:173], v[172:173], 0, s[20:21]
	s_mov_b32 m0, s40
	ds_read_b128 v[180:183], v178 offset:49152
	ds_read_b128 v[184:187], v178 offset:50176
	ds_read_b128 v[188:191], v178 offset:51200
	ds_read_b128 v[192:195], v178 offset:52224
	global_load_lds_dwordx4 v[172:173], off
	s_add_i32 m0, s40, 0x2000
	s_add_u32 s38, s38, 0x80080
	v_lshl_add_u64 v[172:173], v[212:213], 0, s[20:21]
	s_addc_u32 s39, s39, 0
	s_add_i32 s40, s76, s42
	global_load_lds_dwordx4 v[172:173], off
	s_mov_b32 m0, s40
	ds_read_b128 v[208:211], v178 offset:56320
	global_load_lds_dwordx4 v130, s[38:39]
	s_add_i32 m0, s40, 0x2000
	ds_read_b128 v[204:207], v178 offset:55296
	global_load_lds_dwordx4 v134, s[38:39]
	v_lshl_add_u64 v[172:173], v[214:215], 0, s[20:21]
	s_mov_b32 m0, s51
	ds_read_b128 v[200:203], v178 offset:54272
	global_load_lds_dwordx4 v[172:173], off
	v_lshl_add_u64 v[172:173], v[216:217], 0, s[20:21]
	s_mov_b32 m0, s52
	ds_read_b128 v[196:199], v178 offset:53248
	global_load_lds_dwordx4 v[172:173], off
	s_waitcnt vmcnt(8)
	s_waitcnt lgkmcnt(0)
	s_barrier
	s_setprio 1
	v_mfma_i32_16x16x64_i8 v[60:63], v[140:143], v[180:183], v[60:63]
	v_mfma_i32_16x16x64_i8 v[56:59], v[148:151], v[180:183], v[56:59]
	v_mfma_i32_16x16x64_i8 v[52:55], v[140:143], v[188:191], v[52:55]
	v_fmaak_f32 v226, v226, v220, 0x4b400000
	v_mfma_i32_16x16x64_i8 v[48:51], v[148:151], v[188:191], v[48:51]
	v_mfma_i32_16x16x64_i8 v[40:43], v[140:143], v[196:199], v[40:43]
	v_mfma_i32_16x16x64_i8 v[32:35], v[148:151], v[196:199], v[32:35]
	v_fmaak_f32 v227, v227, v225, 0x4b400000
	v_mfma_i32_16x16x64_i8 v[24:27], v[140:143], v[204:207], v[24:27]
	v_mfma_i32_16x16x64_i8 v[16:19], v[148:151], v[204:207], v[16:19]
	v_mfma_i32_16x16x64_i8 v[60:63], v[144:147], v[184:187], v[60:63]
	v_fmaak_f32 v228, v228, v252, 0x4b400000
	v_mfma_i32_16x16x64_i8 v[56:59], v[152:155], v[184:187], v[56:59]
	v_mfma_i32_16x16x64_i8 v[52:55], v[144:147], v[192:195], v[52:55]
	v_mfma_i32_16x16x64_i8 v[48:51], v[152:155], v[192:195], v[48:51]
	v_fmaak_f32 v229, v229, v253, 0x4b400000
	v_mfma_i32_16x16x64_i8 v[40:43], v[144:147], v[200:203], v[40:43]
	v_mfma_i32_16x16x64_i8 v[32:35], v[152:155], v[200:203], v[32:35]
	v_mfma_i32_16x16x64_i8 v[24:27], v[144:147], v[208:211], v[24:27]
	v_alignbit_b32 v239, v226, v239, 8
	v_mfma_i32_16x16x64_i8 v[16:19], v[152:155], v[208:211], v[16:19]
	s_setprio 0
	s_setprio 1
	v_mfma_i32_16x16x64_i8 v[44:47], v[156:159], v[180:183], v[44:47]
	v_mfma_i32_16x16x64_i8 v[36:39], v[164:167], v[180:183], v[36:39]
	v_alignbit_b32 v243, v227, v243, 8
	v_mfma_i32_16x16x64_i8 v[28:31], v[156:159], v[188:191], v[28:31]
	v_mfma_i32_16x16x64_i8 v[20:23], v[164:167], v[188:191], v[20:23]
	v_mfma_i32_16x16x64_i8 v[12:15], v[156:159], v[196:199], v[12:15]
	v_alignbit_b32 v247, v228, v247, 8
	v_mfma_i32_16x16x64_i8 v[8:11], v[164:167], v[196:199], v[8:11]
	v_mfma_i32_16x16x64_i8 v[4:7], v[156:159], v[204:207], v[4:7]
	v_mfma_i32_16x16x64_i8 v[0:3], v[164:167], v[204:207], v[0:3]
	v_alignbit_b32 v251, v229, v251, 8
	v_mfma_i32_16x16x64_i8 v[44:47], v[160:163], v[184:187], v[44:47]
	v_mfma_i32_16x16x64_i8 v[36:39], v[168:171], v[184:187], v[36:39]
	v_mfma_i32_16x16x64_i8 v[28:31], v[160:163], v[192:195], v[28:31]
	v_add_u32_e32 v223, 0x4000, v223
	v_mfma_i32_16x16x64_i8 v[20:23], v[168:171], v[192:195], v[20:23]
	v_mfma_i32_16x16x64_i8 v[12:15], v[160:163], v[200:203], v[12:15]
	v_mfma_i32_16x16x64_i8 v[8:11], v[168:171], v[200:203], v[8:11]
	v_mfma_i32_16x16x64_i8 v[4:7], v[160:163], v[208:211], v[4:7]
	v_mfma_i32_16x16x64_i8 v[0:3], v[168:171], v[208:211], v[0:3]
	s_setprio 0
	s_barrier
	s_cmp_eq_u32 s32, 0
	s_cbranch_scc1 .Lq_mvx_ST
	s_and_b32 s77, s84, 3
	s_cbranch_scc0 .Lq_mv_ST

.LBB0_1474:
	s_add_i32 s75, s48, 2
	s_add_u32 s46, s44, 0x100
	s_addc_u32 s47, s45, 0
	s_cmp_eq_u32 s72, s48
	s_cselect_b32 s51, s41, s47
	s_cselect_b32 s50, s40, s46
	ds_read_b128 v[140:143], v184
	ds_read_b128 v[144:147], v184 offset:1024
	ds_read_b128 v[148:151], v184 offset:2048
	ds_read_b128 v[152:155], v184 offset:3072
	ds_read_b128 v[156:159], v184 offset:16384
	ds_read_b128 v[160:163], v184 offset:17408
	ds_read_b128 v[164:167], v184 offset:18432
	ds_read_b128 v[168:171], v184 offset:19456
	s_cselect_b32 s48, s42, s73
	s_cselect_b32 s49, s43, s74
	s_add_i32 m0, s54, 0xc000
	ds_read_b128 v[172:175], v186
	ds_read_b128 v[176:179], v186 offset:1024
	ds_read_b128 v[188:191], v186 offset:2048
	ds_read_b128 v[192:195], v186 offset:3072
	ds_read_b128 v[196:199], v186 offset:4096
	ds_read_b128 v[200:203], v186 offset:5120
	ds_read_b128 v[204:207], v186 offset:6144
	global_load_lds_dwordx4 v136, s[44:45]
	s_add_i32 m0, s54, 0xe000
	ds_read_b128 v[208:211], v186 offset:7168
	global_load_lds_dwordx4 v138, s[44:45]
	s_waitcnt vmcnt(8)
	s_waitcnt lgkmcnt(0)
	s_barrier
	s_setprio 1
	v_mfma_i32_16x16x64_i8 v[124:127], v[140:143], v[172:175], v[124:127]
	v_mfma_i32_16x16x64_i8 v[120:123], v[148:151], v[172:175], v[120:123]
	v_mfma_i32_16x16x64_i8 v[116:119], v[140:143], v[188:191], v[116:119]
	v_mfma_i32_16x16x64_i8 v[112:115], v[148:151], v[188:191], v[112:115]
	v_mfma_i32_16x16x64_i8 v[104:107], v[140:143], v[196:199], v[104:107]
	v_mfma_i32_16x16x64_i8 v[96:99], v[148:151], v[196:199], v[96:99]
	v_mfma_i32_16x16x64_i8 v[88:91], v[140:143], v[204:207], v[88:91]
	v_mfma_i32_16x16x64_i8 v[80:83], v[148:151], v[204:207], v[80:83]
	v_mfma_i32_16x16x64_i8 v[124:127], v[144:147], v[176:179], v[124:127]
	v_mfma_i32_16x16x64_i8 v[120:123], v[152:155], v[176:179], v[120:123]
	v_mfma_i32_16x16x64_i8 v[116:119], v[144:147], v[192:195], v[116:119]
	v_mfma_i32_16x16x64_i8 v[112:115], v[152:155], v[192:195], v[112:115]
	v_mfma_i32_16x16x64_i8 v[104:107], v[144:147], v[200:203], v[104:107]
	v_mfma_i32_16x16x64_i8 v[96:99], v[152:155], v[200:203], v[96:99]
	v_mfma_i32_16x16x64_i8 v[88:91], v[144:147], v[208:211], v[88:91]
	v_mfma_i32_16x16x64_i8 v[80:83], v[152:155], v[208:211], v[80:83]
	s_setprio 0
	s_setprio 1
	v_mfma_i32_16x16x64_i8 v[108:111], v[156:159], v[172:175], v[108:111]
	v_mfma_i32_16x16x64_i8 v[100:103], v[164:167], v[172:175], v[100:103]
	v_mfma_i32_16x16x64_i8 v[92:95], v[156:159], v[188:191], v[92:95]
	v_mfma_i32_16x16x64_i8 v[84:87], v[164:167], v[188:191], v[84:87]
	v_mfma_i32_16x16x64_i8 v[76:79], v[156:159], v[196:199], v[76:79]
	v_mfma_i32_16x16x64_i8 v[72:75], v[164:167], v[196:199], v[72:75]
	v_mfma_i32_16x16x64_i8 v[68:71], v[156:159], v[204:207], v[68:71]
	v_mfma_i32_16x16x64_i8 v[64:67], v[164:167], v[204:207], v[64:67]
	v_mfma_i32_16x16x64_i8 v[108:111], v[160:163], v[176:179], v[108:111]
	v_mfma_i32_16x16x64_i8 v[100:103], v[168:171], v[176:179], v[100:103]
	v_mfma_i32_16x16x64_i8 v[92:95], v[160:163], v[192:195], v[92:95]
	v_mfma_i32_16x16x64_i8 v[84:87], v[168:171], v[192:195], v[84:87]
	v_mfma_i32_16x16x64_i8 v[76:79], v[160:163], v[200:203], v[76:79]
	v_mfma_i32_16x16x64_i8 v[72:75], v[168:171], v[200:203], v[72:75]
	v_mfma_i32_16x16x64_i8 v[68:71], v[160:163], v[208:211], v[68:71]
	v_mfma_i32_16x16x64_i8 v[64:67], v[168:171], v[208:211], v[64:67]
	s_setprio 0
	s_barrier
	s_add_i32 s44, s66, s53
	s_mov_b32 m0, s44
	ds_read_b128 v[172:175], v186 offset:16384
	ds_read_b128 v[176:179], v186 offset:17408
	ds_read_b128 v[188:191], v186 offset:18432
	ds_read_b128 v[192:195], v186 offset:19456
	global_load_lds_dwordx4 v130, s[48:49]
	s_add_i32 m0, s44, 0x2000
	s_add_u32 s44, s48, 0x158000
	s_addc_u32 s45, s49, 0
	s_add_i32 s76, s67, s53
	global_load_lds_dwordx4 v134, s[48:49]
	s_mov_b32 m0, s76
	ds_read_b128 v[208:211], v186 offset:23552
	global_load_lds_dwordx4 v130, s[44:45]
	s_add_i32 m0, s76, 0x2000
	ds_read_b128 v[204:207], v186 offset:22528
	global_load_lds_dwordx4 v134, s[44:45]
	s_mov_b32 m0, s54
	ds_read_b128 v[200:203], v186 offset:21504
	global_load_lds_dwordx4 v128, s[50:51]
	s_mov_b32 m0, s55
	ds_read_b128 v[196:199], v186 offset:20480
	global_load_lds_dwordx4 v132, s[50:51]
	s_waitcnt vmcnt(8)
	s_waitcnt lgkmcnt(0)
	s_barrier
	s_setprio 1
	v_mfma_i32_16x16x64_i8 v[60:63], v[140:143], v[172:175], v[60:63]
	v_mfma_i32_16x16x64_i8 v[56:59], v[148:151], v[172:175], v[56:59]
	v_mfma_i32_16x16x64_i8 v[52:55], v[140:143], v[188:191], v[52:55]
	v_mfma_i32_16x16x64_i8 v[48:51], v[148:151], v[188:191], v[48:51]
	v_mfma_i32_16x16x64_i8 v[40:43], v[140:143], v[196:199], v[40:43]
	v_mfma_i32_16x16x64_i8 v[32:35], v[148:151], v[196:199], v[32:35]
	v_mfma_i32_16x16x64_i8 v[24:27], v[140:143], v[204:207], v[24:27]
	v_mfma_i32_16x16x64_i8 v[16:19], v[148:151], v[204:207], v[16:19]
	v_mfma_i32_16x16x64_i8 v[60:63], v[144:147], v[176:179], v[60:63]
	v_mfma_i32_16x16x64_i8 v[56:59], v[152:155], v[176:179], v[56:59]
	v_mfma_i32_16x16x64_i8 v[52:55], v[144:147], v[192:195], v[52:55]
	v_mfma_i32_16x16x64_i8 v[48:51], v[152:155], v[192:195], v[48:51]
	v_mfma_i32_16x16x64_i8 v[40:43], v[144:147], v[200:203], v[40:43]
	v_mfma_i32_16x16x64_i8 v[32:35], v[152:155], v[200:203], v[32:35]
	v_mfma_i32_16x16x64_i8 v[24:27], v[144:147], v[208:211], v[24:27]
	v_mfma_i32_16x16x64_i8 v[16:19], v[152:155], v[208:211], v[16:19]
	s_setprio 0
	s_setprio 1
	v_mfma_i32_16x16x64_i8 v[44:47], v[156:159], v[172:175], v[44:47]
	v_mfma_i32_16x16x64_i8 v[36:39], v[164:167], v[172:175], v[36:39]
	v_mfma_i32_16x16x64_i8 v[28:31], v[156:159], v[188:191], v[28:31]
	v_mfma_i32_16x16x64_i8 v[20:23], v[164:167], v[188:191], v[20:23]
	v_mfma_i32_16x16x64_i8 v[12:15], v[156:159], v[196:199], v[12:15]
	v_mfma_i32_16x16x64_i8 v[8:11], v[164:167], v[196:199], v[8:11]
	v_mfma_i32_16x16x64_i8 v[4:7], v[156:159], v[204:207], v[4:7]
	v_mfma_i32_16x16x64_i8 v[0:3], v[164:167], v[204:207], v[0:3]
	v_mfma_i32_16x16x64_i8 v[44:47], v[160:163], v[176:179], v[44:47]
	v_mfma_i32_16x16x64_i8 v[36:39], v[168:171], v[176:179], v[36:39]
	v_mfma_i32_16x16x64_i8 v[28:31], v[160:163], v[192:195], v[28:31]
	v_mfma_i32_16x16x64_i8 v[20:23], v[168:171], v[192:195], v[20:23]
	v_mfma_i32_16x16x64_i8 v[12:15], v[160:163], v[200:203], v[12:15]
	v_mfma_i32_16x16x64_i8 v[8:11], v[168:171], v[200:203], v[8:11]
	v_mfma_i32_16x16x64_i8 v[4:7], v[160:163], v[208:211], v[4:7]
	v_mfma_i32_16x16x64_i8 v[0:3], v[168:171], v[208:211], v[0:3]
	s_setprio 0
	s_barrier
	s_add_i32 s76, 0, 0x18000
	s_add_i32 s77, 0, 0x1c000
	ds_read_b128 v[140:143], v184 offset:32768
	ds_read_b128 v[144:147], v184 offset:33792
	ds_read_b128 v[148:151], v184 offset:34816
	ds_read_b128 v[152:155], v184 offset:35840
	ds_read_b128 v[156:159], v184 offset:49152
	ds_read_b128 v[160:163], v184 offset:50176
	ds_read_b128 v[164:167], v184 offset:51200
	ds_read_b128 v[168:171], v184 offset:52224
	s_add_u32 s44, s50, 0x158000
	s_addc_u32 s45, s51, 0
	s_mov_b32 m0, s60
	ds_read_b128 v[172:175], v186 offset:32768
	ds_read_b128 v[176:179], v186 offset:33792
	ds_read_b128 v[188:191], v186 offset:34816
	ds_read_b128 v[192:195], v186 offset:35840
	ds_read_b128 v[196:199], v186 offset:36864
	ds_read_b128 v[200:203], v186 offset:37888
	ds_read_b128 v[204:207], v186 offset:38912
	global_load_lds_dwordx4 v128, s[44:45]
	s_mov_b32 m0, s61
	ds_read_b128 v[208:211], v186 offset:39936
	global_load_lds_dwordx4 v132, s[44:45]
	s_waitcnt vmcnt(8)
	s_waitcnt lgkmcnt(0)
	s_barrier
	s_setprio 1
	v_mfma_i32_16x16x64_i8 v[124:127], v[140:143], v[172:175], v[124:127]
	v_mfma_i32_16x16x64_i8 v[120:123], v[148:151], v[172:175], v[120:123]
	v_mfma_i32_16x16x64_i8 v[116:119], v[140:143], v[188:191], v[116:119]
	v_mfma_i32_16x16x64_i8 v[112:115], v[148:151], v[188:191], v[112:115]
	v_mfma_i32_16x16x64_i8 v[104:107], v[140:143], v[196:199], v[104:107]
	v_mfma_i32_16x16x64_i8 v[96:99], v[148:151], v[196:199], v[96:99]
	v_mfma_i32_16x16x64_i8 v[88:91], v[140:143], v[204:207], v[88:91]
	v_mfma_i32_16x16x64_i8 v[80:83], v[148:151], v[204:207], v[80:83]
	v_mfma_i32_16x16x64_i8 v[124:127], v[144:147], v[176:179], v[124:127]
	v_mfma_i32_16x16x64_i8 v[120:123], v[152:155], v[176:179], v[120:123]
	v_mfma_i32_16x16x64_i8 v[116:119], v[144:147], v[192:195], v[116:119]
	v_mfma_i32_16x16x64_i8 v[112:115], v[152:155], v[192:195], v[112:115]
	v_mfma_i32_16x16x64_i8 v[104:107], v[144:147], v[200:203], v[104:107]
	v_mfma_i32_16x16x64_i8 v[96:99], v[152:155], v[200:203], v[96:99]
	v_mfma_i32_16x16x64_i8 v[88:91], v[144:147], v[208:211], v[88:91]
	v_mfma_i32_16x16x64_i8 v[80:83], v[152:155], v[208:211], v[80:83]
	s_setprio 0
	s_setprio 1
	v_mfma_i32_16x16x64_i8 v[108:111], v[156:159], v[172:175], v[108:111]
	v_mfma_i32_16x16x64_i8 v[100:103], v[164:167], v[172:175], v[100:103]
	v_mfma_i32_16x16x64_i8 v[92:95], v[156:159], v[188:191], v[92:95]
	v_mfma_i32_16x16x64_i8 v[84:87], v[164:167], v[188:191], v[84:87]
	v_mfma_i32_16x16x64_i8 v[76:79], v[156:159], v[196:199], v[76:79]
	v_mfma_i32_16x16x64_i8 v[72:75], v[164:167], v[196:199], v[72:75]
	v_mfma_i32_16x16x64_i8 v[68:71], v[156:159], v[204:207], v[68:71]
	v_mfma_i32_16x16x64_i8 v[64:67], v[164:167], v[204:207], v[64:67]
	v_mfma_i32_16x16x64_i8 v[108:111], v[160:163], v[176:179], v[108:111]
	v_mfma_i32_16x16x64_i8 v[100:103], v[168:171], v[176:179], v[100:103]
	v_mfma_i32_16x16x64_i8 v[92:95], v[160:163], v[192:195], v[92:95]
	v_mfma_i32_16x16x64_i8 v[84:87], v[168:171], v[192:195], v[84:87]
	v_mfma_i32_16x16x64_i8 v[76:79], v[160:163], v[200:203], v[76:79]
	v_mfma_i32_16x16x64_i8 v[72:75], v[168:171], v[200:203], v[72:75]
	v_mfma_i32_16x16x64_i8 v[68:71], v[160:163], v[208:211], v[68:71]
	v_mfma_i32_16x16x64_i8 v[64:67], v[168:171], v[208:211], v[64:67]
	s_setprio 0
	s_barrier
	s_add_u32 s98, s48, s18
	s_addc_u32 s99, s49, s19
	s_add_u32 s100, s50, s18
	s_addc_u32 s101, s51, s19
	s_add_i32 s44, s76, s53
	s_mov_b32 m0, s44
	ds_read_b128 v[172:175], v186 offset:49152
	ds_read_b128 v[176:179], v186 offset:50176
	ds_read_b128 v[188:191], v186 offset:51200
	ds_read_b128 v[192:195], v186 offset:52224
	global_load_lds_dwordx4 v130, s[98:99]
	s_add_i32 m0, s44, 0x2000
	s_add_u32 s44, s48, 0x158080
	s_addc_u32 s45, s49, 0
	s_add_i32 s48, s77, s53
	global_load_lds_dwordx4 v134, s[98:99]
	s_mov_b32 m0, s48
	ds_read_b128 v[208:211], v186 offset:56320
	global_load_lds_dwordx4 v130, s[44:45]
	s_add_i32 m0, s48, 0x2000
	ds_read_b128 v[204:207], v186 offset:55296
	global_load_lds_dwordx4 v134, s[44:45]
	s_mov_b32 m0, s64
	ds_read_b128 v[200:203], v186 offset:54272
	global_load_lds_dwordx4 v128, s[100:101]
	s_mov_b32 m0, s65
	ds_read_b128 v[196:199], v186 offset:53248
	global_load_lds_dwordx4 v132, s[100:101]
	s_waitcnt vmcnt(8)
	s_waitcnt lgkmcnt(0)
	s_barrier
	s_setprio 1
	v_mfma_i32_16x16x64_i8 v[60:63], v[140:143], v[172:175], v[60:63]
	v_mfma_i32_16x16x64_i8 v[56:59], v[148:151], v[172:175], v[56:59]
	v_mfma_i32_16x16x64_i8 v[52:55], v[140:143], v[188:191], v[52:55]
	v_mfma_i32_16x16x64_i8 v[48:51], v[148:151], v[188:191], v[48:51]
	v_mfma_i32_16x16x64_i8 v[40:43], v[140:143], v[196:199], v[40:43]
	v_mfma_i32_16x16x64_i8 v[32:35], v[148:151], v[196:199], v[32:35]
	v_mfma_i32_16x16x64_i8 v[24:27], v[140:143], v[204:207], v[24:27]
	v_mfma_i32_16x16x64_i8 v[16:19], v[148:151], v[204:207], v[16:19]
	v_mfma_i32_16x16x64_i8 v[60:63], v[144:147], v[176:179], v[60:63]
	v_mfma_i32_16x16x64_i8 v[56:59], v[152:155], v[176:179], v[56:59]
	v_mfma_i32_16x16x64_i8 v[52:55], v[144:147], v[192:195], v[52:55]
	v_mfma_i32_16x16x64_i8 v[48:51], v[152:155], v[192:195], v[48:51]
	v_mfma_i32_16x16x64_i8 v[40:43], v[144:147], v[200:203], v[40:43]
	v_mfma_i32_16x16x64_i8 v[32:35], v[152:155], v[200:203], v[32:35]
	v_mfma_i32_16x16x64_i8 v[24:27], v[144:147], v[208:211], v[24:27]
	v_mfma_i32_16x16x64_i8 v[16:19], v[152:155], v[208:211], v[16:19]
	s_setprio 0
	s_setprio 1
	v_mfma_i32_16x16x64_i8 v[44:47], v[156:159], v[172:175], v[44:47]
	v_mfma_i32_16x16x64_i8 v[36:39], v[164:167], v[172:175], v[36:39]
	v_mfma_i32_16x16x64_i8 v[28:31], v[156:159], v[188:191], v[28:31]
	v_mfma_i32_16x16x64_i8 v[20:23], v[164:167], v[188:191], v[20:23]
	v_mfma_i32_16x16x64_i8 v[12:15], v[156:159], v[196:199], v[12:15]
	v_mfma_i32_16x16x64_i8 v[8:11], v[164:167], v[196:199], v[8:11]
	v_mfma_i32_16x16x64_i8 v[4:7], v[156:159], v[204:207], v[4:7]
	v_mfma_i32_16x16x64_i8 v[0:3], v[164:167], v[204:207], v[0:3]
	v_mfma_i32_16x16x64_i8 v[44:47], v[160:163], v[176:179], v[44:47]
	v_mfma_i32_16x16x64_i8 v[36:39], v[168:171], v[176:179], v[36:39]
	v_mfma_i32_16x16x64_i8 v[28:31], v[160:163], v[192:195], v[28:31]
	v_mfma_i32_16x16x64_i8 v[20:23], v[168:171], v[192:195], v[20:23]
	v_mfma_i32_16x16x64_i8 v[12:15], v[160:163], v[200:203], v[12:15]
	v_mfma_i32_16x16x64_i8 v[8:11], v[168:171], v[200:203], v[8:11]
	v_mfma_i32_16x16x64_i8 v[4:7], v[160:163], v[208:211], v[4:7]
	v_mfma_i32_16x16x64_i8 v[0:3], v[168:171], v[208:211], v[0:3]
	s_setprio 0
	s_barrier
	s_add_u32 s73, s73, 0x100
	s_addc_u32 s74, s74, 0
	s_cmp_ge_i32 s75, s71
	s_mov_b64 s[44:45], s[46:47]
	s_mov_b32 s48, s75
	s_cbranch_scc0 .LBB0_1474
	v_cvt_f32_i32_e32 v140, v124
	v_cvt_f32_i32_e32 v141, v125
	v_cvt_f32_i32_e32 v124, v126
	v_cvt_f32_i32_e32 v125, v127
	v_cvt_f32_i32_e32 v142, v120
	v_cvt_f32_i32_e32 v143, v121
	v_cvt_f32_i32_e32 v126, v122
	v_cvt_f32_i32_e32 v127, v123
	v_cvt_f32_i32_e32 v146, v108
	v_cvt_f32_i32_e32 v147, v109
	v_cvt_f32_i32_e32 v120, v110
	v_cvt_f32_i32_e32 v121, v111
	v_cvt_f32_i32_e32 v148, v100
	v_cvt_f32_i32_e32 v149, v101
	v_cvt_f32_i32_e32 v122, v102
	v_cvt_f32_i32_e32 v123, v103
	v_cvt_f32_i32_e32 v144, v116
	v_cvt_f32_i32_e32 v145, v117
	v_cvt_f32_i32_e32 v116, v118
	v_cvt_f32_i32_e32 v117, v119
	v_cvt_f32_i32_e32 v118, v112
	v_cvt_f32_i32_e32 v119, v113
	v_cvt_f32_i32_e32 v112, v114
	v_cvt_f32_i32_e32 v113, v115
	v_cvt_f32_i32_e32 v152, v92
	v_cvt_f32_i32_e32 v153, v93
	v_cvt_f32_i32_e32 v100, v94
	v_cvt_f32_i32_e32 v101, v95
	v_cvt_f32_i32_e32 v156, v84
	v_cvt_f32_i32_e32 v157, v85
	v_cvt_f32_i32_e32 v102, v86
	v_cvt_f32_i32_e32 v103, v87
	v_cvt_f32_i32_e32 v114, v104
	v_cvt_f32_i32_e32 v115, v105
	v_cvt_f32_i32_e32 v86, v106
	v_cvt_f32_i32_e32 v87, v107
	v_cvt_f32_i32_e32 v150, v96
	v_cvt_f32_i32_e32 v151, v97
	v_cvt_f32_i32_e32 v92, v98
	v_cvt_f32_i32_e32 v93, v99
	v_cvt_f32_i32_e32 v160, v76
	v_cvt_f32_i32_e32 v161, v77
	v_cvt_f32_i32_e32 v84, v78
	v_cvt_f32_i32_e32 v85, v79
	v_cvt_f32_i32_e32 v162, v72
	v_cvt_f32_i32_e32 v163, v73
	v_cvt_f32_i32_e32 v94, v74
	v_cvt_f32_i32_e32 v95, v75
	v_cvt_f32_i32_e32 v154, v88
	v_cvt_f32_i32_e32 v155, v89
	v_cvt_f32_i32_e32 v78, v90
	v_cvt_f32_i32_e32 v79, v91
	v_cvt_f32_i32_e32 v158, v80
	v_cvt_f32_i32_e32 v159, v81
	v_cvt_f32_i32_e32 v80, v82
	v_cvt_f32_i32_e32 v81, v83
	v_cvt_f32_i32_e32 v164, v68
	v_cvt_f32_i32_e32 v165, v69
	v_cvt_f32_i32_e32 v76, v70
	v_cvt_f32_i32_e32 v77, v71
	v_cvt_f32_i32_e32 v166, v64
	v_cvt_f32_i32_e32 v167, v65
	v_cvt_f32_i32_e32 v82, v66
	v_cvt_f32_i32_e32 v83, v67
	v_cvt_f32_i32_e32 v70, v60
	v_cvt_f32_i32_e32 v71, v61
	v_cvt_f32_i32_e32 v74, v62
	v_cvt_f32_i32_e32 v75, v63
	v_cvt_f32_i32_e32 v68, v56
	v_cvt_f32_i32_e32 v69, v57
	v_cvt_f32_i32_e32 v72, v58
	v_cvt_f32_i32_e32 v73, v59
	v_cvt_f32_i32_e32 v62, v44
	v_cvt_f32_i32_e32 v63, v45
	v_cvt_f32_i32_e32 v66, v46
	v_cvt_f32_i32_e32 v67, v47
	v_cvt_f32_i32_e32 v60, v36
	v_cvt_f32_i32_e32 v61, v37
	v_cvt_f32_i32_e32 v64, v38
	v_cvt_f32_i32_e32 v65, v39
	v_cvt_f32_i32_e32 v56, v52
	v_cvt_f32_i32_e32 v57, v53
	v_cvt_f32_i32_e32 v58, v54
	v_cvt_f32_i32_e32 v59, v55
	v_cvt_f32_i32_e32 v52, v48
	v_cvt_f32_i32_e32 v53, v49
	v_cvt_f32_i32_e32 v54, v50
	v_cvt_f32_i32_e32 v55, v51
	v_cvt_f32_i32_e32 v46, v28
	v_cvt_f32_i32_e32 v47, v29
	v_cvt_f32_i32_e32 v50, v30
	v_cvt_f32_i32_e32 v51, v31
	v_cvt_f32_i32_e32 v44, v20
	v_cvt_f32_i32_e32 v45, v21
	v_cvt_f32_i32_e32 v48, v22
	v_cvt_f32_i32_e32 v49, v23
	v_cvt_f32_i32_e32 v38, v40
	v_cvt_f32_i32_e32 v39, v41
	v_cvt_f32_i32_e32 v42, v42
	v_cvt_f32_i32_e32 v43, v43
	v_cvt_f32_i32_e32 v36, v32
	v_cvt_f32_i32_e32 v37, v33
	v_cvt_f32_i32_e32 v40, v34
	v_cvt_f32_i32_e32 v41, v35
	v_cvt_f32_i32_e32 v30, v12
	v_cvt_f32_i32_e32 v31, v13
	v_cvt_f32_i32_e32 v34, v14
	v_cvt_f32_i32_e32 v35, v15
	v_cvt_f32_i32_e32 v28, v8
	v_cvt_f32_i32_e32 v29, v9
	v_cvt_f32_i32_e32 v32, v10
	v_cvt_f32_i32_e32 v33, v11
	v_cvt_f32_i32_e32 v22, v24
	v_cvt_f32_i32_e32 v23, v25
	v_cvt_f32_i32_e32 v26, v26
	v_cvt_f32_i32_e32 v27, v27
	v_cvt_f32_i32_e32 v20, v16
	v_cvt_f32_i32_e32 v21, v17
	v_cvt_f32_i32_e32 v24, v18
	v_cvt_f32_i32_e32 v25, v19
	v_cvt_f32_i32_e32 v14, v4
	v_cvt_f32_i32_e32 v15, v5
	v_cvt_f32_i32_e32 v18, v6
	v_cvt_f32_i32_e32 v19, v7
	v_cvt_f32_i32_e32 v12, v0
	v_cvt_f32_i32_e32 v13, v1
	v_cvt_f32_i32_e32 v16, v2
	v_cvt_f32_i32_e32 v17, v3
	s_and_b64 vcc, exec, s[20:21]
	s_cbranch_vccz .LBB0_1477
